# plus LoRA GEMM epilogue: w0/a0 staged in LDS once per phase instead of 64 global loads each draining the store queue
# baseline (speedup 1.0000x reference)
.LBB0_759:
	s_cmp_lt_i32 s30, 7
	s_cselect_b64 s[8:9], -1, 0
	s_waitcnt lgkmcnt(0)
	s_and_b64 s[12:13], s[8:9], s[6:7]
	s_andn2_b64 vcc, exec, s[12:13]
	s_cbranch_vccnz .LBB0_1174
	s_load_dwordx2 s[88:89], s[0:1], 0x88
	s_load_dwordx2 s[90:91], s[0:1], 0x78
	v_and_b32_e32 v250, 0xff, v231
	v_lshlrev_b32_e32 v251, 4, v231
	v_lshlrev_b32_e32 v250, 4, v250
	v_add_u32_e32 v251, 0x20800, v251
	v_readfirstlane_b32 s87, v230
	s_waitcnt lgkmcnt(0)
	s_nop 2
	s_cmp_lt_u32 s87, 4
	s_cselect_b64 s[92:93], s[88:89], s[90:91]
	global_load_dwordx4 v[246:249], v250, s[92:93]
	s_waitcnt vmcnt(0)
	ds_write_b128 v251, v[246:249]
	s_waitcnt lgkmcnt(0)
	s_barrier
	s_mov_b32 s87, 0x20800
	s_mov_b32 s88, 0x21800
	s_add_u32 s3, s28, 0x2b800000
	s_addc_u32 s44, s29, 0
	s_add_u32 s45, s28, 0xc200000
	s_addc_u32 s46, s29, 0
	s_cmpk_lt_i32 s2, 0x18c
	s_cselect_b64 s[6:7], -1, 0
	s_cmpk_gt_i32 s2, 0x18b
	v_readfirstlane_b32 s24, v231
	s_cbranch_scc1 .LBB0_762
	s_ashr_i32 s8, s2, 31
	s_lshr_b32 s8, s8, 29
	s_add_i32 s8, s2, s8
	s_and_b32 s9, s8, -8
	s_sub_i32 s9, s2, s9
	s_mul_i32 s11, s9, 49
	s_add_i32 s11, s11, 4
	s_ashr_i32 s8, s8, 3
	s_mul_i32 s10, s9, 50
	s_cmp_lt_i32 s9, 4
	s_cselect_b32 s9, s10, s11
	s_add_i32 s9, s9, s8
	s_mul_hi_i32 s8, s9, 0x2aaaaaab
	s_lshr_b32 s10, s8, 31
	s_ashr_i32 s8, s8, 4
	s_add_i32 s8, s8, s10
	s_lshl_b32 s11, s8, 3
	s_sub_i32 s10, 33, s11
	s_mulk_i32 s8, 0x60
	s_min_u32 s14, s10, 8
	s_sub_i32 s15, s9, s8
	s_sext_i32_i8 s8, s15
	v_cvt_f32_ubyte0_e32 v1, s14
	v_cvt_f32_i32_e32 v0, s8
	v_rcp_iflag_f32_e32 v2, v1
	s_ashr_i32 s8, s8, 30
	s_or_b32 s10, s8, 1
	v_mul_f32_e32 v2, v0, v2
	v_trunc_f32_e32 v2, v2
	v_fma_f32 v0, -v2, v1, v0
	v_cvt_i32_f32_e32 v2, v2
	v_cmp_ge_f32_e64 s[8:9], |v0|, v1
	s_and_b64 s[8:9], s[8:9], exec
	s_cselect_b32 s8, s10, 0
	v_readfirstlane_b32 s9, v2
	s_add_i32 s10, s9, s8
	s_mul_i32 s8, s10, s14
	s_sub_i32 s8, s15, s8
	s_sext_i32_i8 s8, s8
	s_add_i32 s14, s11, s8
	s_mul_i32 s8, s14, 0x30000
	s_mul_hi_i32 s9, s14, 0x30000
	s_add_u32 s8, s3, s8
	s_sext_i32_i8 s40, s10
	s_addc_u32 s9, s44, s9
	s_bfe_i64 s[10:11], s[10:11], 0x80000
	s_mul_hi_i32 s11, s10, 0x30000
	s_mul_i32 s10, s10, 0x30000
	s_add_u32 s10, s45, s10
	s_addc_u32 s11, s46, s11
	s_lshl_b32 s75, s14, 8
	s_lshl_b32 s71, s40, 8
	s_andn2_b64 vcc, exec, s[6:7]
	s_cbranch_vccz .LBB0_763
	s_branch .LBB0_1174

.LBB0_782:
	s_andn2_b64 vcc, exec, s[8:9]
	v_mov_b32_e32 v135, v127
	v_mov_b32_e32 v134, v126
	v_mov_b32_e32 v133, v125
	v_mov_b32_e32 v132, v124
	s_cbranch_vccnz .LBB0_784
	v_lshl_add_u32 v128, v175, 2, s87
	ds_read_b128 v[128:131], v128
	s_waitcnt lgkmcnt(0)
	v_add_f32_e32 v128, v124, v128
	v_add_f32_e32 v129, v125, v129
	v_add_f32_e32 v130, v126, v130
	v_add_f32_e32 v131, v127, v131
	v_mul_f32_e32 v128, 0xbfb8aa3b, v128
	v_mul_f32_e32 v129, 0xbfb8aa3b, v129
	v_mul_f32_e32 v130, 0xbfb8aa3b, v130
	v_mul_f32_e32 v131, 0xbfb8aa3b, v131
	v_exp_f32_e32 v128, v128
	v_exp_f32_e32 v129, v129
	v_exp_f32_e32 v130, v130
	v_exp_f32_e32 v131, v131
	v_add_f32_e32 v128, 1.0, v128
	v_add_f32_e32 v129, 1.0, v129
	v_add_f32_e32 v130, 1.0, v130
	v_add_f32_e32 v131, 1.0, v131
	v_rcp_f32_e32 v132, v128
	v_rcp_f32_e32 v133, v129
	v_rcp_f32_e32 v134, v130
	v_rcp_f32_e32 v135, v131
	v_mov_b64_e32 v[128:129], v[132:133]
	v_mov_b64_e32 v[130:131], v[134:135]

.LBB0_785:
	s_andn2_b64 vcc, exec, s[8:9]
	v_lshlrev_b32_e32 v148, 2, v175
	s_cbranch_vccnz .LBB0_787
	v_add_u32_e32 v176, s88, v148
	ds_read_b128 v[128:131], v176
	s_waitcnt lgkmcnt(0)
	v_add_f32_e32 v124, v124, v128
	v_add_f32_e32 v125, v125, v129
	v_add_f32_e32 v126, v126, v130
	v_add_f32_e32 v127, v127, v131
	v_mul_f32_e32 v124, 0xbfb8aa3b, v124
	v_mul_f32_e32 v125, 0xbfb8aa3b, v125
	v_mul_f32_e32 v126, 0xbfb8aa3b, v126
	v_mul_f32_e32 v127, 0xbfb8aa3b, v127
	v_exp_f32_e32 v124, v124
	v_exp_f32_e32 v125, v125
	v_exp_f32_e32 v126, v126
	v_exp_f32_e32 v127, v127
	v_add_f32_e32 v124, 1.0, v124
	v_add_f32_e32 v125, 1.0, v125
	v_add_f32_e32 v126, 1.0, v126
	v_add_f32_e32 v127, 1.0, v127
	v_rcp_f32_e32 v124, v124
	v_rcp_f32_e32 v125, v125
	v_rcp_f32_e32 v126, v126
	v_rcp_f32_e32 v127, v127
	v_mul_f32_e32 v124, 0xbf1b4598, v124
	v_mul_f32_e32 v125, 0xbf1b4598, v125
	v_mul_f32_e32 v126, 0xbf1b4598, v126
	v_mul_f32_e32 v127, 0xbf1b4598, v127
	v_mul_f32_e32 v124, 0x3fb8aa3b, v124
	v_mul_f32_e32 v125, 0x3fb8aa3b, v125
	v_mul_f32_e32 v126, 0x3fb8aa3b, v126
	v_mul_f32_e32 v127, 0x3fb8aa3b, v127
	v_exp_f32_e32 v128, v124
	v_exp_f32_e32 v129, v125
	v_exp_f32_e32 v130, v126
	v_exp_f32_e32 v131, v127
	v_mov_b32_e32 v132, v128
	v_mov_b32_e32 v133, v129
	v_mov_b32_e32 v134, v130
	v_mov_b32_e32 v135, v131

.LBB0_810:
	s_andn2_b64 vcc, exec, s[40:41]
	v_mov_b32_e32 v119, v111
	v_mov_b32_e32 v118, v110
	v_mov_b32_e32 v117, v109
	v_mov_b32_e32 v116, v108
	s_cbranch_vccnz .LBB0_812
	v_lshl_add_u32 v112, v175, 2, s87
	ds_read_b128 v[112:115], v112
	s_waitcnt lgkmcnt(0)
	v_add_f32_e32 v112, v108, v112
	v_add_f32_e32 v113, v109, v113
	v_add_f32_e32 v114, v110, v114
	v_add_f32_e32 v115, v111, v115
	v_mul_f32_e32 v112, 0xbfb8aa3b, v112
	v_mul_f32_e32 v113, 0xbfb8aa3b, v113
	v_mul_f32_e32 v114, 0xbfb8aa3b, v114
	v_mul_f32_e32 v115, 0xbfb8aa3b, v115
	v_exp_f32_e32 v112, v112
	v_exp_f32_e32 v113, v113
	v_exp_f32_e32 v114, v114
	v_exp_f32_e32 v115, v115
	v_add_f32_e32 v112, 1.0, v112
	v_add_f32_e32 v113, 1.0, v113
	v_add_f32_e32 v114, 1.0, v114
	v_add_f32_e32 v115, 1.0, v115
	v_rcp_f32_e32 v116, v112
	v_rcp_f32_e32 v117, v113
	v_rcp_f32_e32 v118, v114
	v_rcp_f32_e32 v119, v115
	v_mov_b64_e32 v[112:113], v[116:117]
	v_mov_b64_e32 v[114:115], v[118:119]

.LBB0_813:
	s_andn2_b64 vcc, exec, s[40:41]
	v_lshlrev_b32_e32 v148, 2, v175
	s_cbranch_vccnz .LBB0_815
	v_add_u32_e32 v176, s88, v148
	ds_read_b128 v[112:115], v176
	s_waitcnt lgkmcnt(0)
	v_add_f32_e32 v108, v108, v112
	v_add_f32_e32 v109, v109, v113
	v_add_f32_e32 v110, v110, v114
	v_add_f32_e32 v111, v111, v115
	v_mul_f32_e32 v108, 0xbfb8aa3b, v108
	v_mul_f32_e32 v109, 0xbfb8aa3b, v109
	v_mul_f32_e32 v110, 0xbfb8aa3b, v110
	v_mul_f32_e32 v111, 0xbfb8aa3b, v111
	v_exp_f32_e32 v108, v108
	v_exp_f32_e32 v109, v109
	v_exp_f32_e32 v110, v110
	v_exp_f32_e32 v111, v111
	v_add_f32_e32 v108, 1.0, v108
	v_add_f32_e32 v109, 1.0, v109
	v_add_f32_e32 v110, 1.0, v110
	v_add_f32_e32 v111, 1.0, v111
	v_rcp_f32_e32 v108, v108
	v_rcp_f32_e32 v109, v109
	v_rcp_f32_e32 v110, v110
	v_rcp_f32_e32 v111, v111
	v_mul_f32_e32 v108, 0xbf1b4598, v108
	v_mul_f32_e32 v109, 0xbf1b4598, v109
	v_mul_f32_e32 v110, 0xbf1b4598, v110
	v_mul_f32_e32 v111, 0xbf1b4598, v111
	v_mul_f32_e32 v108, 0x3fb8aa3b, v108
	v_mul_f32_e32 v109, 0x3fb8aa3b, v109
	v_mul_f32_e32 v110, 0x3fb8aa3b, v110
	v_mul_f32_e32 v111, 0x3fb8aa3b, v111
	v_exp_f32_e32 v112, v108
	v_exp_f32_e32 v113, v109
	v_exp_f32_e32 v114, v110
	v_exp_f32_e32 v115, v111
	v_mov_b32_e32 v116, v112
	v_mov_b32_e32 v117, v113
	v_mov_b32_e32 v118, v114
	v_mov_b32_e32 v119, v115

.LBB0_838:
	s_andn2_b64 vcc, exec, s[40:41]
	v_mov_b32_e32 v103, v95
	v_mov_b32_e32 v102, v94
	v_mov_b32_e32 v101, v93
	v_mov_b32_e32 v100, v92
	s_cbranch_vccnz .LBB0_840
	v_lshl_add_u32 v96, v175, 2, s87
	ds_read_b128 v[96:99], v96
	s_waitcnt lgkmcnt(0)
	v_add_f32_e32 v96, v92, v96
	v_add_f32_e32 v97, v93, v97
	v_add_f32_e32 v98, v94, v98
	v_add_f32_e32 v99, v95, v99
	v_mul_f32_e32 v96, 0xbfb8aa3b, v96
	v_mul_f32_e32 v97, 0xbfb8aa3b, v97
	v_mul_f32_e32 v98, 0xbfb8aa3b, v98
	v_mul_f32_e32 v99, 0xbfb8aa3b, v99
	v_exp_f32_e32 v96, v96
	v_exp_f32_e32 v97, v97
	v_exp_f32_e32 v98, v98
	v_exp_f32_e32 v99, v99
	v_add_f32_e32 v96, 1.0, v96
	v_add_f32_e32 v97, 1.0, v97
	v_add_f32_e32 v98, 1.0, v98
	v_add_f32_e32 v99, 1.0, v99
	v_rcp_f32_e32 v100, v96
	v_rcp_f32_e32 v101, v97
	v_rcp_f32_e32 v102, v98
	v_rcp_f32_e32 v103, v99
	v_mov_b64_e32 v[96:97], v[100:101]
	v_mov_b64_e32 v[98:99], v[102:103]

.LBB0_841:
	s_andn2_b64 vcc, exec, s[40:41]
	v_lshlrev_b32_e32 v148, 2, v175
	s_cbranch_vccnz .LBB0_843
	v_add_u32_e32 v176, s88, v148
	ds_read_b128 v[96:99], v176
	s_waitcnt lgkmcnt(0)
	v_add_f32_e32 v92, v92, v96
	v_add_f32_e32 v93, v93, v97
	v_add_f32_e32 v94, v94, v98
	v_add_f32_e32 v95, v95, v99
	v_mul_f32_e32 v92, 0xbfb8aa3b, v92
	v_mul_f32_e32 v93, 0xbfb8aa3b, v93
	v_mul_f32_e32 v94, 0xbfb8aa3b, v94
	v_mul_f32_e32 v95, 0xbfb8aa3b, v95
	v_exp_f32_e32 v92, v92
	v_exp_f32_e32 v93, v93
	v_exp_f32_e32 v94, v94
	v_exp_f32_e32 v95, v95
	v_add_f32_e32 v92, 1.0, v92
	v_add_f32_e32 v93, 1.0, v93
	v_add_f32_e32 v94, 1.0, v94
	v_add_f32_e32 v95, 1.0, v95
	v_rcp_f32_e32 v92, v92
	v_rcp_f32_e32 v93, v93
	v_rcp_f32_e32 v94, v94
	v_rcp_f32_e32 v95, v95
	v_mul_f32_e32 v92, 0xbf1b4598, v92
	v_mul_f32_e32 v93, 0xbf1b4598, v93
	v_mul_f32_e32 v94, 0xbf1b4598, v94
	v_mul_f32_e32 v95, 0xbf1b4598, v95
	v_mul_f32_e32 v92, 0x3fb8aa3b, v92
	v_mul_f32_e32 v93, 0x3fb8aa3b, v93
	v_mul_f32_e32 v94, 0x3fb8aa3b, v94
	v_mul_f32_e32 v95, 0x3fb8aa3b, v95
	v_exp_f32_e32 v96, v92
	v_exp_f32_e32 v97, v93
	v_exp_f32_e32 v98, v94
	v_exp_f32_e32 v99, v95
	v_mov_b32_e32 v100, v96
	v_mov_b32_e32 v101, v97
	v_mov_b32_e32 v102, v98
	v_mov_b32_e32 v103, v99

.LBB0_866:
	s_andn2_b64 vcc, exec, s[40:41]
	v_mov_b32_e32 v87, v79
	v_mov_b32_e32 v86, v78
	v_mov_b32_e32 v85, v77
	v_mov_b32_e32 v84, v76
	s_cbranch_vccnz .LBB0_868
	v_lshl_add_u32 v80, v175, 2, s87
	ds_read_b128 v[80:83], v80
	s_waitcnt lgkmcnt(0)
	v_add_f32_e32 v80, v76, v80
	v_add_f32_e32 v81, v77, v81
	v_add_f32_e32 v82, v78, v82
	v_add_f32_e32 v83, v79, v83
	v_mul_f32_e32 v80, 0xbfb8aa3b, v80
	v_mul_f32_e32 v81, 0xbfb8aa3b, v81
	v_mul_f32_e32 v82, 0xbfb8aa3b, v82
	v_mul_f32_e32 v83, 0xbfb8aa3b, v83
	v_exp_f32_e32 v80, v80
	v_exp_f32_e32 v81, v81
	v_exp_f32_e32 v82, v82
	v_exp_f32_e32 v83, v83
	v_add_f32_e32 v80, 1.0, v80
	v_add_f32_e32 v81, 1.0, v81
	v_add_f32_e32 v82, 1.0, v82
	v_add_f32_e32 v83, 1.0, v83
	v_rcp_f32_e32 v84, v80
	v_rcp_f32_e32 v85, v81
	v_rcp_f32_e32 v86, v82
	v_rcp_f32_e32 v87, v83
	v_mov_b64_e32 v[80:81], v[84:85]
	v_mov_b64_e32 v[82:83], v[86:87]

.LBB0_869:
	s_andn2_b64 vcc, exec, s[40:41]
	v_lshlrev_b32_e32 v148, 2, v175
	s_cbranch_vccnz .LBB0_871
	v_add_u32_e32 v176, s88, v148
	ds_read_b128 v[80:83], v176
	s_waitcnt lgkmcnt(0)
	v_add_f32_e32 v76, v76, v80
	v_add_f32_e32 v77, v77, v81
	v_add_f32_e32 v78, v78, v82
	v_add_f32_e32 v79, v79, v83
	v_mul_f32_e32 v76, 0xbfb8aa3b, v76
	v_mul_f32_e32 v77, 0xbfb8aa3b, v77
	v_mul_f32_e32 v78, 0xbfb8aa3b, v78
	v_mul_f32_e32 v79, 0xbfb8aa3b, v79
	v_exp_f32_e32 v76, v76
	v_exp_f32_e32 v77, v77
	v_exp_f32_e32 v78, v78
	v_exp_f32_e32 v79, v79
	v_add_f32_e32 v76, 1.0, v76
	v_add_f32_e32 v77, 1.0, v77
	v_add_f32_e32 v78, 1.0, v78
	v_add_f32_e32 v79, 1.0, v79
	v_rcp_f32_e32 v76, v76
	v_rcp_f32_e32 v77, v77
	v_rcp_f32_e32 v78, v78
	v_rcp_f32_e32 v79, v79
	v_mul_f32_e32 v76, 0xbf1b4598, v76
	v_mul_f32_e32 v77, 0xbf1b4598, v77
	v_mul_f32_e32 v78, 0xbf1b4598, v78
	v_mul_f32_e32 v79, 0xbf1b4598, v79
	v_mul_f32_e32 v76, 0x3fb8aa3b, v76
	v_mul_f32_e32 v77, 0x3fb8aa3b, v77
	v_mul_f32_e32 v78, 0x3fb8aa3b, v78
	v_mul_f32_e32 v79, 0x3fb8aa3b, v79
	v_exp_f32_e32 v80, v76
	v_exp_f32_e32 v81, v77
	v_exp_f32_e32 v82, v78
	v_exp_f32_e32 v83, v79
	v_mov_b32_e32 v84, v80
	v_mov_b32_e32 v85, v81
	v_mov_b32_e32 v86, v82
	v_mov_b32_e32 v87, v83

.LBB0_894:
	s_andn2_b64 vcc, exec, s[40:41]
	v_mov_b32_e32 v71, v63
	v_mov_b32_e32 v70, v62
	v_mov_b32_e32 v69, v61
	v_mov_b32_e32 v68, v60
	s_cbranch_vccnz .LBB0_896
	v_lshl_add_u32 v64, v175, 2, s87
	ds_read_b128 v[64:67], v64
	s_waitcnt lgkmcnt(0)
	v_add_f32_e32 v64, v60, v64
	v_add_f32_e32 v65, v61, v65
	v_add_f32_e32 v66, v62, v66
	v_add_f32_e32 v67, v63, v67
	v_mul_f32_e32 v64, 0xbfb8aa3b, v64
	v_mul_f32_e32 v65, 0xbfb8aa3b, v65
	v_mul_f32_e32 v66, 0xbfb8aa3b, v66
	v_mul_f32_e32 v67, 0xbfb8aa3b, v67
	v_exp_f32_e32 v64, v64
	v_exp_f32_e32 v65, v65
	v_exp_f32_e32 v66, v66
	v_exp_f32_e32 v67, v67
	v_add_f32_e32 v64, 1.0, v64
	v_add_f32_e32 v65, 1.0, v65
	v_add_f32_e32 v66, 1.0, v66
	v_add_f32_e32 v67, 1.0, v67
	v_rcp_f32_e32 v68, v64
	v_rcp_f32_e32 v69, v65
	v_rcp_f32_e32 v70, v66
	v_rcp_f32_e32 v71, v67
	v_mov_b64_e32 v[64:65], v[68:69]
	v_mov_b64_e32 v[66:67], v[70:71]

.LBB0_897:
	s_andn2_b64 vcc, exec, s[40:41]
	v_lshlrev_b32_e32 v148, 2, v175
	s_cbranch_vccnz .LBB0_899
	v_add_u32_e32 v176, s88, v148
	ds_read_b128 v[64:67], v176
	s_waitcnt lgkmcnt(0)
	v_add_f32_e32 v60, v60, v64
	v_add_f32_e32 v61, v61, v65
	v_add_f32_e32 v62, v62, v66
	v_add_f32_e32 v63, v63, v67
	v_mul_f32_e32 v60, 0xbfb8aa3b, v60
	v_mul_f32_e32 v61, 0xbfb8aa3b, v61
	v_mul_f32_e32 v62, 0xbfb8aa3b, v62
	v_mul_f32_e32 v63, 0xbfb8aa3b, v63
	v_exp_f32_e32 v60, v60
	v_exp_f32_e32 v61, v61
	v_exp_f32_e32 v62, v62
	v_exp_f32_e32 v63, v63
	v_add_f32_e32 v60, 1.0, v60
	v_add_f32_e32 v61, 1.0, v61
	v_add_f32_e32 v62, 1.0, v62
	v_add_f32_e32 v63, 1.0, v63
	v_rcp_f32_e32 v60, v60
	v_rcp_f32_e32 v61, v61
	v_rcp_f32_e32 v62, v62
	v_rcp_f32_e32 v63, v63
	v_mul_f32_e32 v60, 0xbf1b4598, v60
	v_mul_f32_e32 v61, 0xbf1b4598, v61
	v_mul_f32_e32 v62, 0xbf1b4598, v62
	v_mul_f32_e32 v63, 0xbf1b4598, v63
	v_mul_f32_e32 v60, 0x3fb8aa3b, v60
	v_mul_f32_e32 v61, 0x3fb8aa3b, v61
	v_mul_f32_e32 v62, 0x3fb8aa3b, v62
	v_mul_f32_e32 v63, 0x3fb8aa3b, v63
	v_exp_f32_e32 v64, v60
	v_exp_f32_e32 v65, v61
	v_exp_f32_e32 v66, v62
	v_exp_f32_e32 v67, v63
	v_mov_b32_e32 v68, v64
	v_mov_b32_e32 v69, v65
	v_mov_b32_e32 v70, v66
	v_mov_b32_e32 v71, v67

.LBB0_922:
	s_andn2_b64 vcc, exec, s[40:41]
	v_mov_b32_e32 v55, v47
	v_mov_b32_e32 v54, v46
	v_mov_b32_e32 v53, v45
	v_mov_b32_e32 v52, v44
	s_cbranch_vccnz .LBB0_924
	v_lshl_add_u32 v48, v175, 2, s87
	ds_read_b128 v[48:51], v48
	s_waitcnt lgkmcnt(0)
	v_add_f32_e32 v48, v44, v48
	v_add_f32_e32 v49, v45, v49
	v_add_f32_e32 v50, v46, v50
	v_add_f32_e32 v51, v47, v51
	v_mul_f32_e32 v48, 0xbfb8aa3b, v48
	v_mul_f32_e32 v49, 0xbfb8aa3b, v49
	v_mul_f32_e32 v50, 0xbfb8aa3b, v50
	v_mul_f32_e32 v51, 0xbfb8aa3b, v51
	v_exp_f32_e32 v48, v48
	v_exp_f32_e32 v49, v49
	v_exp_f32_e32 v50, v50
	v_exp_f32_e32 v51, v51
	v_add_f32_e32 v48, 1.0, v48
	v_add_f32_e32 v49, 1.0, v49
	v_add_f32_e32 v50, 1.0, v50
	v_add_f32_e32 v51, 1.0, v51
	v_rcp_f32_e32 v52, v48
	v_rcp_f32_e32 v53, v49
	v_rcp_f32_e32 v54, v50
	v_rcp_f32_e32 v55, v51
	v_mov_b64_e32 v[48:49], v[52:53]
	v_mov_b64_e32 v[50:51], v[54:55]

.LBB0_925:
	s_andn2_b64 vcc, exec, s[40:41]
	v_lshlrev_b32_e32 v148, 2, v175
	s_cbranch_vccnz .LBB0_927
	v_add_u32_e32 v176, s88, v148
	ds_read_b128 v[48:51], v176
	s_waitcnt lgkmcnt(0)
	v_add_f32_e32 v44, v44, v48
	v_add_f32_e32 v45, v45, v49
	v_add_f32_e32 v46, v46, v50
	v_add_f32_e32 v47, v47, v51
	v_mul_f32_e32 v44, 0xbfb8aa3b, v44
	v_mul_f32_e32 v45, 0xbfb8aa3b, v45
	v_mul_f32_e32 v46, 0xbfb8aa3b, v46
	v_mul_f32_e32 v47, 0xbfb8aa3b, v47
	v_exp_f32_e32 v44, v44
	v_exp_f32_e32 v45, v45
	v_exp_f32_e32 v46, v46
	v_exp_f32_e32 v47, v47
	v_add_f32_e32 v44, 1.0, v44
	v_add_f32_e32 v45, 1.0, v45
	v_add_f32_e32 v46, 1.0, v46
	v_add_f32_e32 v47, 1.0, v47
	v_rcp_f32_e32 v44, v44
	v_rcp_f32_e32 v45, v45
	v_rcp_f32_e32 v46, v46
	v_rcp_f32_e32 v47, v47
	v_mul_f32_e32 v44, 0xbf1b4598, v44
	v_mul_f32_e32 v45, 0xbf1b4598, v45
	v_mul_f32_e32 v46, 0xbf1b4598, v46
	v_mul_f32_e32 v47, 0xbf1b4598, v47
	v_mul_f32_e32 v44, 0x3fb8aa3b, v44
	v_mul_f32_e32 v45, 0x3fb8aa3b, v45
	v_mul_f32_e32 v46, 0x3fb8aa3b, v46
	v_mul_f32_e32 v47, 0x3fb8aa3b, v47
	v_exp_f32_e32 v48, v44
	v_exp_f32_e32 v49, v45
	v_exp_f32_e32 v50, v46
	v_exp_f32_e32 v51, v47
	v_mov_b32_e32 v52, v48
	v_mov_b32_e32 v53, v49
	v_mov_b32_e32 v54, v50
	v_mov_b32_e32 v55, v51

.LBB0_950:
	s_andn2_b64 vcc, exec, s[40:41]
	v_mov_b32_e32 v39, v31
	v_mov_b32_e32 v38, v30
	v_mov_b32_e32 v37, v29
	v_mov_b32_e32 v36, v28
	s_cbranch_vccnz .LBB0_952
	v_lshl_add_u32 v32, v175, 2, s87
	ds_read_b128 v[32:35], v32
	s_waitcnt lgkmcnt(0)
	v_add_f32_e32 v32, v28, v32
	v_add_f32_e32 v33, v29, v33
	v_add_f32_e32 v34, v30, v34
	v_add_f32_e32 v35, v31, v35
	v_mul_f32_e32 v32, 0xbfb8aa3b, v32
	v_mul_f32_e32 v33, 0xbfb8aa3b, v33
	v_mul_f32_e32 v34, 0xbfb8aa3b, v34
	v_mul_f32_e32 v35, 0xbfb8aa3b, v35
	v_exp_f32_e32 v32, v32
	v_exp_f32_e32 v33, v33
	v_exp_f32_e32 v34, v34
	v_exp_f32_e32 v35, v35
	v_add_f32_e32 v32, 1.0, v32
	v_add_f32_e32 v33, 1.0, v33
	v_add_f32_e32 v34, 1.0, v34
	v_add_f32_e32 v35, 1.0, v35
	v_rcp_f32_e32 v36, v32
	v_rcp_f32_e32 v37, v33
	v_rcp_f32_e32 v38, v34
	v_rcp_f32_e32 v39, v35
	v_mov_b64_e32 v[32:33], v[36:37]
	v_mov_b64_e32 v[34:35], v[38:39]

.LBB0_953:
	s_andn2_b64 vcc, exec, s[40:41]
	v_lshlrev_b32_e32 v148, 2, v175
	s_cbranch_vccnz .LBB0_955
	v_add_u32_e32 v176, s88, v148
	ds_read_b128 v[32:35], v176
	s_waitcnt lgkmcnt(0)
	v_add_f32_e32 v28, v28, v32
	v_add_f32_e32 v29, v29, v33
	v_add_f32_e32 v30, v30, v34
	v_add_f32_e32 v31, v31, v35
	v_mul_f32_e32 v28, 0xbfb8aa3b, v28
	v_mul_f32_e32 v29, 0xbfb8aa3b, v29
	v_mul_f32_e32 v30, 0xbfb8aa3b, v30
	v_mul_f32_e32 v31, 0xbfb8aa3b, v31
	v_exp_f32_e32 v28, v28
	v_exp_f32_e32 v29, v29
	v_exp_f32_e32 v30, v30
	v_exp_f32_e32 v31, v31
	v_add_f32_e32 v28, 1.0, v28
	v_add_f32_e32 v29, 1.0, v29
	v_add_f32_e32 v30, 1.0, v30
	v_add_f32_e32 v31, 1.0, v31
	v_rcp_f32_e32 v28, v28
	v_rcp_f32_e32 v29, v29
	v_rcp_f32_e32 v30, v30
	v_rcp_f32_e32 v31, v31
	v_mul_f32_e32 v28, 0xbf1b4598, v28
	v_mul_f32_e32 v29, 0xbf1b4598, v29
	v_mul_f32_e32 v30, 0xbf1b4598, v30
	v_mul_f32_e32 v31, 0xbf1b4598, v31
	v_mul_f32_e32 v28, 0x3fb8aa3b, v28
	v_mul_f32_e32 v29, 0x3fb8aa3b, v29
	v_mul_f32_e32 v30, 0x3fb8aa3b, v30
	v_mul_f32_e32 v31, 0x3fb8aa3b, v31
	v_exp_f32_e32 v32, v28
	v_exp_f32_e32 v33, v29
	v_exp_f32_e32 v34, v30
	v_exp_f32_e32 v35, v31
	v_mov_b32_e32 v36, v32
	v_mov_b32_e32 v37, v33
	v_mov_b32_e32 v38, v34
	v_mov_b32_e32 v39, v35

.LBB0_978:
	s_andn2_b64 vcc, exec, s[40:41]
	v_mov_b32_e32 v23, v15
	v_mov_b32_e32 v22, v14
	v_mov_b32_e32 v21, v13
	v_mov_b32_e32 v20, v12
	s_cbranch_vccnz .LBB0_980
	v_lshl_add_u32 v16, v175, 2, s87
	ds_read_b128 v[16:19], v16
	s_waitcnt lgkmcnt(0)
	v_add_f32_e32 v16, v12, v16
	v_add_f32_e32 v17, v13, v17
	v_add_f32_e32 v18, v14, v18
	v_add_f32_e32 v19, v15, v19
	v_mul_f32_e32 v16, 0xbfb8aa3b, v16
	v_mul_f32_e32 v17, 0xbfb8aa3b, v17
	v_mul_f32_e32 v18, 0xbfb8aa3b, v18
	v_mul_f32_e32 v19, 0xbfb8aa3b, v19
	v_exp_f32_e32 v16, v16
	v_exp_f32_e32 v17, v17
	v_exp_f32_e32 v18, v18
	v_exp_f32_e32 v19, v19
	v_add_f32_e32 v16, 1.0, v16
	v_add_f32_e32 v17, 1.0, v17
	v_add_f32_e32 v18, 1.0, v18
	v_add_f32_e32 v19, 1.0, v19
	v_rcp_f32_e32 v20, v16
	v_rcp_f32_e32 v21, v17
	v_rcp_f32_e32 v22, v18
	v_rcp_f32_e32 v23, v19
	v_mov_b64_e32 v[16:17], v[20:21]
	v_mov_b64_e32 v[18:19], v[22:23]

.LBB0_981:
	s_andn2_b64 vcc, exec, s[40:41]
	v_lshlrev_b32_e32 v148, 2, v175
	s_cbranch_vccnz .LBB0_983
	v_add_u32_e32 v176, s88, v148
	ds_read_b128 v[16:19], v176
	s_waitcnt lgkmcnt(0)
	v_add_f32_e32 v12, v12, v16
	v_add_f32_e32 v13, v13, v17
	v_add_f32_e32 v14, v14, v18
	v_add_f32_e32 v15, v15, v19
	v_mul_f32_e32 v12, 0xbfb8aa3b, v12
	v_mul_f32_e32 v13, 0xbfb8aa3b, v13
	v_mul_f32_e32 v14, 0xbfb8aa3b, v14
	v_mul_f32_e32 v15, 0xbfb8aa3b, v15
	v_exp_f32_e32 v12, v12
	v_exp_f32_e32 v13, v13
	v_exp_f32_e32 v14, v14
	v_exp_f32_e32 v15, v15
	v_add_f32_e32 v12, 1.0, v12
	v_add_f32_e32 v13, 1.0, v13
	v_add_f32_e32 v14, 1.0, v14
	v_add_f32_e32 v15, 1.0, v15
	v_rcp_f32_e32 v12, v12
	v_rcp_f32_e32 v13, v13
	v_rcp_f32_e32 v14, v14
	v_rcp_f32_e32 v15, v15
	v_mul_f32_e32 v12, 0xbf1b4598, v12
	v_mul_f32_e32 v13, 0xbf1b4598, v13
	v_mul_f32_e32 v14, 0xbf1b4598, v14
	v_mul_f32_e32 v15, 0xbf1b4598, v15
	v_mul_f32_e32 v12, 0x3fb8aa3b, v12
	v_mul_f32_e32 v13, 0x3fb8aa3b, v13
	v_mul_f32_e32 v14, 0x3fb8aa3b, v14
	v_mul_f32_e32 v15, 0x3fb8aa3b, v15
	v_exp_f32_e32 v16, v12
	v_exp_f32_e32 v17, v13
	v_exp_f32_e32 v18, v14
	v_exp_f32_e32 v19, v15
	v_mov_b32_e32 v20, v16
	v_mov_b32_e32 v21, v17
	v_mov_b32_e32 v22, v18
	v_mov_b32_e32 v23, v19

.LBB0_1007:
	s_andn2_b64 vcc, exec, s[42:43]
	v_mov_b32_e32 v131, v123
	v_mov_b32_e32 v130, v122
	v_mov_b32_e32 v129, v121
	v_mov_b32_e32 v128, v120
	s_cbranch_vccnz .LBB0_1009
	v_lshl_add_u32 v124, v135, 2, s87
	ds_read_b128 v[124:127], v124
	s_waitcnt lgkmcnt(0)
	v_add_f32_e32 v124, v120, v124
	v_add_f32_e32 v125, v121, v125
	v_add_f32_e32 v126, v122, v126
	v_add_f32_e32 v127, v123, v127
	v_mul_f32_e32 v124, 0xbfb8aa3b, v124
	v_mul_f32_e32 v125, 0xbfb8aa3b, v125
	v_mul_f32_e32 v126, 0xbfb8aa3b, v126
	v_mul_f32_e32 v127, 0xbfb8aa3b, v127
	v_exp_f32_e32 v124, v124
	v_exp_f32_e32 v125, v125
	v_exp_f32_e32 v126, v126
	v_exp_f32_e32 v127, v127
	v_add_f32_e32 v124, 1.0, v124
	v_add_f32_e32 v125, 1.0, v125
	v_add_f32_e32 v126, 1.0, v126
	v_add_f32_e32 v127, 1.0, v127
	v_rcp_f32_e32 v128, v124
	v_rcp_f32_e32 v129, v125
	v_rcp_f32_e32 v130, v126
	v_rcp_f32_e32 v131, v127
	v_mov_b64_e32 v[124:125], v[128:129]
	v_mov_b64_e32 v[126:127], v[130:131]

.LBB0_1010:
	v_add_u32_e32 v176, s88, v148
	ds_read_b128 v[124:127], v176
	s_waitcnt lgkmcnt(0)
	v_add_f32_e32 v120, v120, v124
	v_add_f32_e32 v121, v121, v125
	v_add_f32_e32 v122, v122, v126
	v_add_f32_e32 v123, v123, v127
	v_mul_f32_e32 v120, 0xbfb8aa3b, v120
	v_mul_f32_e32 v121, 0xbfb8aa3b, v121
	v_mul_f32_e32 v122, 0xbfb8aa3b, v122
	v_mul_f32_e32 v123, 0xbfb8aa3b, v123
	v_exp_f32_e32 v120, v120
	v_exp_f32_e32 v121, v121
	v_exp_f32_e32 v122, v122
	v_exp_f32_e32 v123, v123
	v_add_f32_e32 v120, 1.0, v120
	v_add_f32_e32 v121, 1.0, v121
	v_add_f32_e32 v122, 1.0, v122
	v_add_f32_e32 v123, 1.0, v123
	v_rcp_f32_e32 v120, v120
	v_rcp_f32_e32 v121, v121
	v_rcp_f32_e32 v122, v122
	v_rcp_f32_e32 v123, v123
	v_mul_f32_e32 v120, 0xbf1b4598, v120
	v_mul_f32_e32 v121, 0xbf1b4598, v121
	v_mul_f32_e32 v122, 0xbf1b4598, v122
	v_mul_f32_e32 v123, 0xbf1b4598, v123
	v_mul_f32_e32 v120, 0x3fb8aa3b, v120
	v_mul_f32_e32 v121, 0x3fb8aa3b, v121
	v_mul_f32_e32 v122, 0x3fb8aa3b, v122
	v_mul_f32_e32 v123, 0x3fb8aa3b, v123
	v_exp_f32_e32 v124, v120
	v_exp_f32_e32 v125, v121
	v_exp_f32_e32 v126, v122
	v_exp_f32_e32 v127, v123
	v_mov_b32_e32 v128, v124
	v_mov_b32_e32 v129, v125
	v_mov_b32_e32 v130, v126
	v_mov_b32_e32 v131, v127
	s_and_b64 vcc, exec, s[8:9]
	s_mov_b64 s[42:43], -1
	s_cbranch_vccnz .LBB0_794

.LBB0_1014:
	s_andn2_b64 vcc, exec, s[42:43]
	v_mov_b32_e32 v127, v119
	v_mov_b32_e32 v126, v118
	v_mov_b32_e32 v125, v117
	v_mov_b32_e32 v124, v116
	s_cbranch_vccnz .LBB0_1016
	v_lshl_add_u32 v120, v129, 2, s87
	ds_read_b128 v[120:123], v120
	s_waitcnt lgkmcnt(0)
	v_add_f32_e32 v120, v116, v120
	v_add_f32_e32 v121, v117, v121
	v_add_f32_e32 v122, v118, v122
	v_add_f32_e32 v123, v119, v123
	v_mul_f32_e32 v120, 0xbfb8aa3b, v120
	v_mul_f32_e32 v121, 0xbfb8aa3b, v121
	v_mul_f32_e32 v122, 0xbfb8aa3b, v122
	v_mul_f32_e32 v123, 0xbfb8aa3b, v123
	v_exp_f32_e32 v120, v120
	v_exp_f32_e32 v121, v121
	v_exp_f32_e32 v122, v122
	v_exp_f32_e32 v123, v123
	v_add_f32_e32 v120, 1.0, v120
	v_add_f32_e32 v121, 1.0, v121
	v_add_f32_e32 v122, 1.0, v122
	v_add_f32_e32 v123, 1.0, v123
	v_rcp_f32_e32 v124, v120
	v_rcp_f32_e32 v125, v121
	v_rcp_f32_e32 v126, v122
	v_rcp_f32_e32 v127, v123
	v_mov_b64_e32 v[120:121], v[124:125]
	v_mov_b64_e32 v[122:123], v[126:127]

.LBB0_1017:
	v_add_u32_e32 v176, s88, v148
	ds_read_b128 v[120:123], v176
	s_waitcnt lgkmcnt(0)
	v_add_f32_e32 v116, v116, v120
	v_add_f32_e32 v117, v117, v121
	v_add_f32_e32 v118, v118, v122
	v_add_f32_e32 v119, v119, v123
	v_mul_f32_e32 v116, 0xbfb8aa3b, v116
	v_mul_f32_e32 v117, 0xbfb8aa3b, v117
	v_mul_f32_e32 v118, 0xbfb8aa3b, v118
	v_mul_f32_e32 v119, 0xbfb8aa3b, v119
	v_exp_f32_e32 v116, v116
	v_exp_f32_e32 v117, v117
	v_exp_f32_e32 v118, v118
	v_exp_f32_e32 v119, v119
	v_add_f32_e32 v116, 1.0, v116
	v_add_f32_e32 v117, 1.0, v117
	v_add_f32_e32 v118, 1.0, v118
	v_add_f32_e32 v119, 1.0, v119
	v_rcp_f32_e32 v116, v116
	v_rcp_f32_e32 v117, v117
	v_rcp_f32_e32 v118, v118
	v_rcp_f32_e32 v119, v119
	v_mul_f32_e32 v116, 0xbf1b4598, v116
	v_mul_f32_e32 v117, 0xbf1b4598, v117
	v_mul_f32_e32 v118, 0xbf1b4598, v118
	v_mul_f32_e32 v119, 0xbf1b4598, v119
	v_mul_f32_e32 v116, 0x3fb8aa3b, v116
	v_mul_f32_e32 v117, 0x3fb8aa3b, v117
	v_mul_f32_e32 v118, 0x3fb8aa3b, v118
	v_mul_f32_e32 v119, 0x3fb8aa3b, v119
	v_exp_f32_e32 v120, v116
	v_exp_f32_e32 v121, v117
	v_exp_f32_e32 v122, v118
	v_exp_f32_e32 v123, v119
	v_mov_b32_e32 v124, v120
	v_mov_b32_e32 v125, v121
	v_mov_b32_e32 v126, v122
	v_mov_b32_e32 v127, v123
	s_and_b64 vcc, exec, s[8:9]
	s_mov_b64 s[42:43], -1
	s_cbranch_vccnz .LBB0_799

.LBB0_1021:
	s_andn2_b64 vcc, exec, s[42:43]
	v_mov_b32_e32 v123, v115
	v_mov_b32_e32 v122, v114
	v_mov_b32_e32 v121, v113
	v_mov_b32_e32 v120, v112
	s_cbranch_vccnz .LBB0_1023
	v_lshl_add_u32 v116, v125, 2, s87
	ds_read_b128 v[116:119], v116
	s_waitcnt lgkmcnt(0)
	v_add_f32_e32 v116, v112, v116
	v_add_f32_e32 v117, v113, v117
	v_add_f32_e32 v118, v114, v118
	v_add_f32_e32 v119, v115, v119
	v_mul_f32_e32 v116, 0xbfb8aa3b, v116
	v_mul_f32_e32 v117, 0xbfb8aa3b, v117
	v_mul_f32_e32 v118, 0xbfb8aa3b, v118
	v_mul_f32_e32 v119, 0xbfb8aa3b, v119
	v_exp_f32_e32 v116, v116
	v_exp_f32_e32 v117, v117
	v_exp_f32_e32 v118, v118
	v_exp_f32_e32 v119, v119
	v_add_f32_e32 v116, 1.0, v116
	v_add_f32_e32 v117, 1.0, v117
	v_add_f32_e32 v118, 1.0, v118
	v_add_f32_e32 v119, 1.0, v119
	v_rcp_f32_e32 v120, v116
	v_rcp_f32_e32 v121, v117
	v_rcp_f32_e32 v122, v118
	v_rcp_f32_e32 v123, v119
	v_mov_b64_e32 v[116:117], v[120:121]
	v_mov_b64_e32 v[118:119], v[122:123]

.LBB0_1024:
	v_add_u32_e32 v176, s88, v148
	ds_read_b128 v[116:119], v176
	s_waitcnt lgkmcnt(0)
	v_add_f32_e32 v112, v112, v116
	v_add_f32_e32 v113, v113, v117
	v_add_f32_e32 v114, v114, v118
	v_add_f32_e32 v115, v115, v119
	v_mul_f32_e32 v112, 0xbfb8aa3b, v112
	v_mul_f32_e32 v113, 0xbfb8aa3b, v113
	v_mul_f32_e32 v114, 0xbfb8aa3b, v114
	v_mul_f32_e32 v115, 0xbfb8aa3b, v115
	v_exp_f32_e32 v112, v112
	v_exp_f32_e32 v113, v113
	v_exp_f32_e32 v114, v114
	v_exp_f32_e32 v115, v115
	v_add_f32_e32 v112, 1.0, v112
	v_add_f32_e32 v113, 1.0, v113
	v_add_f32_e32 v114, 1.0, v114
	v_add_f32_e32 v115, 1.0, v115
	v_rcp_f32_e32 v112, v112
	v_rcp_f32_e32 v113, v113
	v_rcp_f32_e32 v114, v114
	v_rcp_f32_e32 v115, v115
	v_mul_f32_e32 v112, 0xbf1b4598, v112
	v_mul_f32_e32 v113, 0xbf1b4598, v113
	v_mul_f32_e32 v114, 0xbf1b4598, v114
	v_mul_f32_e32 v115, 0xbf1b4598, v115
	v_mul_f32_e32 v112, 0x3fb8aa3b, v112
	v_mul_f32_e32 v113, 0x3fb8aa3b, v113
	v_mul_f32_e32 v114, 0x3fb8aa3b, v114
	v_mul_f32_e32 v115, 0x3fb8aa3b, v115
	v_exp_f32_e32 v116, v112
	v_exp_f32_e32 v117, v113
	v_exp_f32_e32 v118, v114
	v_exp_f32_e32 v119, v115
	v_mov_b32_e32 v120, v116
	v_mov_b32_e32 v121, v117
	v_mov_b32_e32 v122, v118
	v_mov_b32_e32 v123, v119
	s_and_b64 vcc, exec, s[8:9]
	s_mov_b64 s[8:9], -1
	s_cbranch_vccnz .LBB0_804

.LBB0_1028:
	s_andn2_b64 vcc, exec, s[40:41]
	v_mov_b32_e32 v115, v107
	v_mov_b32_e32 v114, v106
	v_mov_b32_e32 v113, v105
	v_mov_b32_e32 v112, v104
	s_cbranch_vccnz .LBB0_1030
	v_lshl_add_u32 v108, v119, 2, s87
	ds_read_b128 v[108:111], v108
	s_waitcnt lgkmcnt(0)
	v_add_f32_e32 v108, v104, v108
	v_add_f32_e32 v109, v105, v109
	v_add_f32_e32 v110, v106, v110
	v_add_f32_e32 v111, v107, v111
	v_mul_f32_e32 v108, 0xbfb8aa3b, v108
	v_mul_f32_e32 v109, 0xbfb8aa3b, v109
	v_mul_f32_e32 v110, 0xbfb8aa3b, v110
	v_mul_f32_e32 v111, 0xbfb8aa3b, v111
	v_exp_f32_e32 v108, v108
	v_exp_f32_e32 v109, v109
	v_exp_f32_e32 v110, v110
	v_exp_f32_e32 v111, v111
	v_add_f32_e32 v108, 1.0, v108
	v_add_f32_e32 v109, 1.0, v109
	v_add_f32_e32 v110, 1.0, v110
	v_add_f32_e32 v111, 1.0, v111
	v_rcp_f32_e32 v112, v108
	v_rcp_f32_e32 v113, v109
	v_rcp_f32_e32 v114, v110
	v_rcp_f32_e32 v115, v111
	v_mov_b64_e32 v[108:109], v[112:113]
	v_mov_b64_e32 v[110:111], v[114:115]

.LBB0_1031:
	v_add_u32_e32 v176, s88, v148
	ds_read_b128 v[108:111], v176
	s_waitcnt lgkmcnt(0)
	v_add_f32_e32 v104, v104, v108
	v_add_f32_e32 v105, v105, v109
	v_add_f32_e32 v106, v106, v110
	v_add_f32_e32 v107, v107, v111
	v_mul_f32_e32 v104, 0xbfb8aa3b, v104
	v_mul_f32_e32 v105, 0xbfb8aa3b, v105
	v_mul_f32_e32 v106, 0xbfb8aa3b, v106
	v_mul_f32_e32 v107, 0xbfb8aa3b, v107
	v_exp_f32_e32 v104, v104
	v_exp_f32_e32 v105, v105
	v_exp_f32_e32 v106, v106
	v_exp_f32_e32 v107, v107
	v_add_f32_e32 v104, 1.0, v104
	v_add_f32_e32 v105, 1.0, v105
	v_add_f32_e32 v106, 1.0, v106
	v_add_f32_e32 v107, 1.0, v107
	v_rcp_f32_e32 v104, v104
	v_rcp_f32_e32 v105, v105
	v_rcp_f32_e32 v106, v106
	v_rcp_f32_e32 v107, v107
	v_mul_f32_e32 v104, 0xbf1b4598, v104
	v_mul_f32_e32 v105, 0xbf1b4598, v105
	v_mul_f32_e32 v106, 0xbf1b4598, v106
	v_mul_f32_e32 v107, 0xbf1b4598, v107
	v_mul_f32_e32 v104, 0x3fb8aa3b, v104
	v_mul_f32_e32 v105, 0x3fb8aa3b, v105
	v_mul_f32_e32 v106, 0x3fb8aa3b, v106
	v_mul_f32_e32 v107, 0x3fb8aa3b, v107
	v_exp_f32_e32 v108, v104
	v_exp_f32_e32 v109, v105
	v_exp_f32_e32 v110, v106
	v_exp_f32_e32 v111, v107
	v_mov_b32_e32 v112, v108
	v_mov_b32_e32 v113, v109
	v_mov_b32_e32 v114, v110
	v_mov_b32_e32 v115, v111
	s_and_b64 vcc, exec, s[8:9]
	s_mov_b64 s[40:41], -1
	s_cbranch_vccnz .LBB0_822

.LBB0_1035:
	s_andn2_b64 vcc, exec, s[40:41]
	v_mov_b32_e32 v111, v103
	v_mov_b32_e32 v110, v102
	v_mov_b32_e32 v109, v101
	v_mov_b32_e32 v108, v100
	s_cbranch_vccnz .LBB0_1037
	v_lshl_add_u32 v104, v113, 2, s87
	ds_read_b128 v[104:107], v104
	s_waitcnt lgkmcnt(0)
	v_add_f32_e32 v104, v100, v104
	v_add_f32_e32 v105, v101, v105
	v_add_f32_e32 v106, v102, v106
	v_add_f32_e32 v107, v103, v107
	v_mul_f32_e32 v104, 0xbfb8aa3b, v104
	v_mul_f32_e32 v105, 0xbfb8aa3b, v105
	v_mul_f32_e32 v106, 0xbfb8aa3b, v106
	v_mul_f32_e32 v107, 0xbfb8aa3b, v107
	v_exp_f32_e32 v104, v104
	v_exp_f32_e32 v105, v105
	v_exp_f32_e32 v106, v106
	v_exp_f32_e32 v107, v107
	v_add_f32_e32 v104, 1.0, v104
	v_add_f32_e32 v105, 1.0, v105
	v_add_f32_e32 v106, 1.0, v106
	v_add_f32_e32 v107, 1.0, v107
	v_rcp_f32_e32 v108, v104
	v_rcp_f32_e32 v109, v105
	v_rcp_f32_e32 v110, v106
	v_rcp_f32_e32 v111, v107
	v_mov_b64_e32 v[104:105], v[108:109]
	v_mov_b64_e32 v[106:107], v[110:111]

.LBB0_1038:
	v_add_u32_e32 v176, s88, v148
	ds_read_b128 v[104:107], v176
	s_waitcnt lgkmcnt(0)
	v_add_f32_e32 v100, v100, v104
	v_add_f32_e32 v101, v101, v105
	v_add_f32_e32 v102, v102, v106
	v_add_f32_e32 v103, v103, v107
	v_mul_f32_e32 v100, 0xbfb8aa3b, v100
	v_mul_f32_e32 v101, 0xbfb8aa3b, v101
	v_mul_f32_e32 v102, 0xbfb8aa3b, v102
	v_mul_f32_e32 v103, 0xbfb8aa3b, v103
	v_exp_f32_e32 v100, v100
	v_exp_f32_e32 v101, v101
	v_exp_f32_e32 v102, v102
	v_exp_f32_e32 v103, v103
	v_add_f32_e32 v100, 1.0, v100
	v_add_f32_e32 v101, 1.0, v101
	v_add_f32_e32 v102, 1.0, v102
	v_add_f32_e32 v103, 1.0, v103
	v_rcp_f32_e32 v100, v100
	v_rcp_f32_e32 v101, v101
	v_rcp_f32_e32 v102, v102
	v_rcp_f32_e32 v103, v103
	v_mul_f32_e32 v100, 0xbf1b4598, v100
	v_mul_f32_e32 v101, 0xbf1b4598, v101
	v_mul_f32_e32 v102, 0xbf1b4598, v102
	v_mul_f32_e32 v103, 0xbf1b4598, v103
	v_mul_f32_e32 v100, 0x3fb8aa3b, v100
	v_mul_f32_e32 v101, 0x3fb8aa3b, v101
	v_mul_f32_e32 v102, 0x3fb8aa3b, v102
	v_mul_f32_e32 v103, 0x3fb8aa3b, v103
	v_exp_f32_e32 v104, v100
	v_exp_f32_e32 v105, v101
	v_exp_f32_e32 v106, v102
	v_exp_f32_e32 v107, v103
	v_mov_b32_e32 v108, v104
	v_mov_b32_e32 v109, v105
	v_mov_b32_e32 v110, v106
	v_mov_b32_e32 v111, v107
	s_and_b64 vcc, exec, s[8:9]
	s_mov_b64 s[40:41], -1
	s_cbranch_vccnz .LBB0_827

.LBB0_1042:
	s_andn2_b64 vcc, exec, s[40:41]
	v_mov_b32_e32 v107, v99
	v_mov_b32_e32 v106, v98
	v_mov_b32_e32 v105, v97
	v_mov_b32_e32 v104, v96
	s_cbranch_vccnz .LBB0_1044
	v_lshl_add_u32 v100, v109, 2, s87
	ds_read_b128 v[100:103], v100
	s_waitcnt lgkmcnt(0)
	v_add_f32_e32 v100, v96, v100
	v_add_f32_e32 v101, v97, v101
	v_add_f32_e32 v102, v98, v102
	v_add_f32_e32 v103, v99, v103
	v_mul_f32_e32 v100, 0xbfb8aa3b, v100
	v_mul_f32_e32 v101, 0xbfb8aa3b, v101
	v_mul_f32_e32 v102, 0xbfb8aa3b, v102
	v_mul_f32_e32 v103, 0xbfb8aa3b, v103
	v_exp_f32_e32 v100, v100
	v_exp_f32_e32 v101, v101
	v_exp_f32_e32 v102, v102
	v_exp_f32_e32 v103, v103
	v_add_f32_e32 v100, 1.0, v100
	v_add_f32_e32 v101, 1.0, v101
	v_add_f32_e32 v102, 1.0, v102
	v_add_f32_e32 v103, 1.0, v103
	v_rcp_f32_e32 v104, v100
	v_rcp_f32_e32 v105, v101
	v_rcp_f32_e32 v106, v102
	v_rcp_f32_e32 v107, v103
	v_mov_b64_e32 v[100:101], v[104:105]
	v_mov_b64_e32 v[102:103], v[106:107]

.LBB0_1045:
	v_add_u32_e32 v176, s88, v148
	ds_read_b128 v[100:103], v176
	s_waitcnt lgkmcnt(0)
	v_add_f32_e32 v96, v96, v100
	v_add_f32_e32 v97, v97, v101
	v_add_f32_e32 v98, v98, v102
	v_add_f32_e32 v99, v99, v103
	v_mul_f32_e32 v96, 0xbfb8aa3b, v96
	v_mul_f32_e32 v97, 0xbfb8aa3b, v97
	v_mul_f32_e32 v98, 0xbfb8aa3b, v98
	v_mul_f32_e32 v99, 0xbfb8aa3b, v99
	v_exp_f32_e32 v96, v96
	v_exp_f32_e32 v97, v97
	v_exp_f32_e32 v98, v98
	v_exp_f32_e32 v99, v99
	v_add_f32_e32 v96, 1.0, v96
	v_add_f32_e32 v97, 1.0, v97
	v_add_f32_e32 v98, 1.0, v98
	v_add_f32_e32 v99, 1.0, v99
	v_rcp_f32_e32 v96, v96
	v_rcp_f32_e32 v97, v97
	v_rcp_f32_e32 v98, v98
	v_rcp_f32_e32 v99, v99
	v_mul_f32_e32 v96, 0xbf1b4598, v96
	v_mul_f32_e32 v97, 0xbf1b4598, v97
	v_mul_f32_e32 v98, 0xbf1b4598, v98
	v_mul_f32_e32 v99, 0xbf1b4598, v99
	v_mul_f32_e32 v96, 0x3fb8aa3b, v96
	v_mul_f32_e32 v97, 0x3fb8aa3b, v97
	v_mul_f32_e32 v98, 0x3fb8aa3b, v98
	v_mul_f32_e32 v99, 0x3fb8aa3b, v99
	v_exp_f32_e32 v100, v96
	v_exp_f32_e32 v101, v97
	v_exp_f32_e32 v102, v98
	v_exp_f32_e32 v103, v99
	v_mov_b32_e32 v104, v100
	v_mov_b32_e32 v105, v101
	v_mov_b32_e32 v106, v102
	v_mov_b32_e32 v107, v103
	s_and_b64 vcc, exec, s[8:9]
	s_mov_b64 s[40:41], -1
	s_cbranch_vccnz .LBB0_832

.LBB0_1049:
	s_andn2_b64 vcc, exec, s[40:41]
	v_mov_b32_e32 v99, v91
	v_mov_b32_e32 v98, v90
	v_mov_b32_e32 v97, v89
	v_mov_b32_e32 v96, v88
	s_cbranch_vccnz .LBB0_1051
	v_lshl_add_u32 v92, v103, 2, s87
	ds_read_b128 v[92:95], v92
	s_waitcnt lgkmcnt(0)
	v_add_f32_e32 v92, v88, v92
	v_add_f32_e32 v93, v89, v93
	v_add_f32_e32 v94, v90, v94
	v_add_f32_e32 v95, v91, v95
	v_mul_f32_e32 v92, 0xbfb8aa3b, v92
	v_mul_f32_e32 v93, 0xbfb8aa3b, v93
	v_mul_f32_e32 v94, 0xbfb8aa3b, v94
	v_mul_f32_e32 v95, 0xbfb8aa3b, v95
	v_exp_f32_e32 v92, v92
	v_exp_f32_e32 v93, v93
	v_exp_f32_e32 v94, v94
	v_exp_f32_e32 v95, v95
	v_add_f32_e32 v92, 1.0, v92
	v_add_f32_e32 v93, 1.0, v93
	v_add_f32_e32 v94, 1.0, v94
	v_add_f32_e32 v95, 1.0, v95
	v_rcp_f32_e32 v96, v92
	v_rcp_f32_e32 v97, v93
	v_rcp_f32_e32 v98, v94
	v_rcp_f32_e32 v99, v95
	v_mov_b64_e32 v[92:93], v[96:97]
	v_mov_b64_e32 v[94:95], v[98:99]

.LBB0_1052:
	v_add_u32_e32 v176, s88, v148
	ds_read_b128 v[92:95], v176
	s_waitcnt lgkmcnt(0)
	v_add_f32_e32 v88, v88, v92
	v_add_f32_e32 v89, v89, v93
	v_add_f32_e32 v90, v90, v94
	v_add_f32_e32 v91, v91, v95
	v_mul_f32_e32 v88, 0xbfb8aa3b, v88
	v_mul_f32_e32 v89, 0xbfb8aa3b, v89
	v_mul_f32_e32 v90, 0xbfb8aa3b, v90
	v_mul_f32_e32 v91, 0xbfb8aa3b, v91
	v_exp_f32_e32 v88, v88
	v_exp_f32_e32 v89, v89
	v_exp_f32_e32 v90, v90
	v_exp_f32_e32 v91, v91
	v_add_f32_e32 v88, 1.0, v88
	v_add_f32_e32 v89, 1.0, v89
	v_add_f32_e32 v90, 1.0, v90
	v_add_f32_e32 v91, 1.0, v91
	v_rcp_f32_e32 v88, v88
	v_rcp_f32_e32 v89, v89
	v_rcp_f32_e32 v90, v90
	v_rcp_f32_e32 v91, v91
	v_mul_f32_e32 v88, 0xbf1b4598, v88
	v_mul_f32_e32 v89, 0xbf1b4598, v89
	v_mul_f32_e32 v90, 0xbf1b4598, v90
	v_mul_f32_e32 v91, 0xbf1b4598, v91
	v_mul_f32_e32 v88, 0x3fb8aa3b, v88
	v_mul_f32_e32 v89, 0x3fb8aa3b, v89
	v_mul_f32_e32 v90, 0x3fb8aa3b, v90
	v_mul_f32_e32 v91, 0x3fb8aa3b, v91
	v_exp_f32_e32 v92, v88
	v_exp_f32_e32 v93, v89
	v_exp_f32_e32 v94, v90
	v_exp_f32_e32 v95, v91
	v_mov_b32_e32 v96, v92
	v_mov_b32_e32 v97, v93
	v_mov_b32_e32 v98, v94
	v_mov_b32_e32 v99, v95
	s_and_b64 vcc, exec, s[8:9]
	s_mov_b64 s[40:41], -1
	s_cbranch_vccnz .LBB0_850

.LBB0_1056:
	s_andn2_b64 vcc, exec, s[40:41]
	v_mov_b32_e32 v95, v87
	v_mov_b32_e32 v94, v86
	v_mov_b32_e32 v93, v85
	v_mov_b32_e32 v92, v84
	s_cbranch_vccnz .LBB0_1058
	v_lshl_add_u32 v88, v97, 2, s87
	ds_read_b128 v[88:91], v88
	s_waitcnt lgkmcnt(0)
	v_add_f32_e32 v88, v84, v88
	v_add_f32_e32 v89, v85, v89
	v_add_f32_e32 v90, v86, v90
	v_add_f32_e32 v91, v87, v91
	v_mul_f32_e32 v88, 0xbfb8aa3b, v88
	v_mul_f32_e32 v89, 0xbfb8aa3b, v89
	v_mul_f32_e32 v90, 0xbfb8aa3b, v90
	v_mul_f32_e32 v91, 0xbfb8aa3b, v91
	v_exp_f32_e32 v88, v88
	v_exp_f32_e32 v89, v89
	v_exp_f32_e32 v90, v90
	v_exp_f32_e32 v91, v91
	v_add_f32_e32 v88, 1.0, v88
	v_add_f32_e32 v89, 1.0, v89
	v_add_f32_e32 v90, 1.0, v90
	v_add_f32_e32 v91, 1.0, v91
	v_rcp_f32_e32 v92, v88
	v_rcp_f32_e32 v93, v89
	v_rcp_f32_e32 v94, v90
	v_rcp_f32_e32 v95, v91
	v_mov_b64_e32 v[88:89], v[92:93]
	v_mov_b64_e32 v[90:91], v[94:95]

.LBB0_1059:
	v_add_u32_e32 v176, s88, v148
	ds_read_b128 v[88:91], v176
	s_waitcnt lgkmcnt(0)
	v_add_f32_e32 v84, v84, v88
	v_add_f32_e32 v85, v85, v89
	v_add_f32_e32 v86, v86, v90
	v_add_f32_e32 v87, v87, v91
	v_mul_f32_e32 v84, 0xbfb8aa3b, v84
	v_mul_f32_e32 v85, 0xbfb8aa3b, v85
	v_mul_f32_e32 v86, 0xbfb8aa3b, v86
	v_mul_f32_e32 v87, 0xbfb8aa3b, v87
	v_exp_f32_e32 v84, v84
	v_exp_f32_e32 v85, v85
	v_exp_f32_e32 v86, v86
	v_exp_f32_e32 v87, v87
	v_add_f32_e32 v84, 1.0, v84
	v_add_f32_e32 v85, 1.0, v85
	v_add_f32_e32 v86, 1.0, v86
	v_add_f32_e32 v87, 1.0, v87
	v_rcp_f32_e32 v84, v84
	v_rcp_f32_e32 v85, v85
	v_rcp_f32_e32 v86, v86
	v_rcp_f32_e32 v87, v87
	v_mul_f32_e32 v84, 0xbf1b4598, v84
	v_mul_f32_e32 v85, 0xbf1b4598, v85
	v_mul_f32_e32 v86, 0xbf1b4598, v86
	v_mul_f32_e32 v87, 0xbf1b4598, v87
	v_mul_f32_e32 v84, 0x3fb8aa3b, v84
	v_mul_f32_e32 v85, 0x3fb8aa3b, v85
	v_mul_f32_e32 v86, 0x3fb8aa3b, v86
	v_mul_f32_e32 v87, 0x3fb8aa3b, v87
	v_exp_f32_e32 v88, v84
	v_exp_f32_e32 v89, v85
	v_exp_f32_e32 v90, v86
	v_exp_f32_e32 v91, v87
	v_mov_b32_e32 v92, v88
	v_mov_b32_e32 v93, v89
	v_mov_b32_e32 v94, v90
	v_mov_b32_e32 v95, v91
	s_and_b64 vcc, exec, s[8:9]
	s_mov_b64 s[40:41], -1
	s_cbranch_vccnz .LBB0_855

.LBB0_1063:
	s_andn2_b64 vcc, exec, s[40:41]
	v_mov_b32_e32 v91, v83
	v_mov_b32_e32 v90, v82
	v_mov_b32_e32 v89, v81
	v_mov_b32_e32 v88, v80
	s_cbranch_vccnz .LBB0_1065
	v_lshl_add_u32 v84, v93, 2, s87
	ds_read_b128 v[84:87], v84
	s_waitcnt lgkmcnt(0)
	v_add_f32_e32 v84, v80, v84
	v_add_f32_e32 v85, v81, v85
	v_add_f32_e32 v86, v82, v86
	v_add_f32_e32 v87, v83, v87
	v_mul_f32_e32 v84, 0xbfb8aa3b, v84
	v_mul_f32_e32 v85, 0xbfb8aa3b, v85
	v_mul_f32_e32 v86, 0xbfb8aa3b, v86
	v_mul_f32_e32 v87, 0xbfb8aa3b, v87
	v_exp_f32_e32 v84, v84
	v_exp_f32_e32 v85, v85
	v_exp_f32_e32 v86, v86
	v_exp_f32_e32 v87, v87
	v_add_f32_e32 v84, 1.0, v84
	v_add_f32_e32 v85, 1.0, v85
	v_add_f32_e32 v86, 1.0, v86
	v_add_f32_e32 v87, 1.0, v87
	v_rcp_f32_e32 v88, v84
	v_rcp_f32_e32 v89, v85
	v_rcp_f32_e32 v90, v86
	v_rcp_f32_e32 v91, v87
	v_mov_b64_e32 v[84:85], v[88:89]
	v_mov_b64_e32 v[86:87], v[90:91]

.LBB0_1066:
	v_add_u32_e32 v176, s88, v148
	ds_read_b128 v[84:87], v176
	s_waitcnt lgkmcnt(0)
	v_add_f32_e32 v80, v80, v84
	v_add_f32_e32 v81, v81, v85
	v_add_f32_e32 v82, v82, v86
	v_add_f32_e32 v83, v83, v87
	v_mul_f32_e32 v80, 0xbfb8aa3b, v80
	v_mul_f32_e32 v81, 0xbfb8aa3b, v81
	v_mul_f32_e32 v82, 0xbfb8aa3b, v82
	v_mul_f32_e32 v83, 0xbfb8aa3b, v83
	v_exp_f32_e32 v80, v80
	v_exp_f32_e32 v81, v81
	v_exp_f32_e32 v82, v82
	v_exp_f32_e32 v83, v83
	v_add_f32_e32 v80, 1.0, v80
	v_add_f32_e32 v81, 1.0, v81
	v_add_f32_e32 v82, 1.0, v82
	v_add_f32_e32 v83, 1.0, v83
	v_rcp_f32_e32 v80, v80
	v_rcp_f32_e32 v81, v81
	v_rcp_f32_e32 v82, v82
	v_rcp_f32_e32 v83, v83
	v_mul_f32_e32 v80, 0xbf1b4598, v80
	v_mul_f32_e32 v81, 0xbf1b4598, v81
	v_mul_f32_e32 v82, 0xbf1b4598, v82
	v_mul_f32_e32 v83, 0xbf1b4598, v83
	v_mul_f32_e32 v80, 0x3fb8aa3b, v80
	v_mul_f32_e32 v81, 0x3fb8aa3b, v81
	v_mul_f32_e32 v82, 0x3fb8aa3b, v82
	v_mul_f32_e32 v83, 0x3fb8aa3b, v83
	v_exp_f32_e32 v84, v80
	v_exp_f32_e32 v85, v81
	v_exp_f32_e32 v86, v82
	v_exp_f32_e32 v87, v83
	v_mov_b32_e32 v88, v84
	v_mov_b32_e32 v89, v85
	v_mov_b32_e32 v90, v86
	v_mov_b32_e32 v91, v87
	s_and_b64 vcc, exec, s[8:9]
	s_mov_b64 s[40:41], -1
	s_cbranch_vccnz .LBB0_860

.LBB0_1070:
	s_andn2_b64 vcc, exec, s[40:41]
	v_mov_b32_e32 v83, v75
	v_mov_b32_e32 v82, v74
	v_mov_b32_e32 v81, v73
	v_mov_b32_e32 v80, v72
	s_cbranch_vccnz .LBB0_1072
	v_lshl_add_u32 v76, v87, 2, s87
	ds_read_b128 v[76:79], v76
	s_waitcnt lgkmcnt(0)
	v_add_f32_e32 v76, v72, v76
	v_add_f32_e32 v77, v73, v77
	v_add_f32_e32 v78, v74, v78
	v_add_f32_e32 v79, v75, v79
	v_mul_f32_e32 v76, 0xbfb8aa3b, v76
	v_mul_f32_e32 v77, 0xbfb8aa3b, v77
	v_mul_f32_e32 v78, 0xbfb8aa3b, v78
	v_mul_f32_e32 v79, 0xbfb8aa3b, v79
	v_exp_f32_e32 v76, v76
	v_exp_f32_e32 v77, v77
	v_exp_f32_e32 v78, v78
	v_exp_f32_e32 v79, v79
	v_add_f32_e32 v76, 1.0, v76
	v_add_f32_e32 v77, 1.0, v77
	v_add_f32_e32 v78, 1.0, v78
	v_add_f32_e32 v79, 1.0, v79
	v_rcp_f32_e32 v80, v76
	v_rcp_f32_e32 v81, v77
	v_rcp_f32_e32 v82, v78
	v_rcp_f32_e32 v83, v79
	v_mov_b64_e32 v[76:77], v[80:81]
	v_mov_b64_e32 v[78:79], v[82:83]

.LBB0_1073:
	v_add_u32_e32 v176, s88, v148
	ds_read_b128 v[76:79], v176
	s_waitcnt lgkmcnt(0)
	v_add_f32_e32 v72, v72, v76
	v_add_f32_e32 v73, v73, v77
	v_add_f32_e32 v74, v74, v78
	v_add_f32_e32 v75, v75, v79
	v_mul_f32_e32 v72, 0xbfb8aa3b, v72
	v_mul_f32_e32 v73, 0xbfb8aa3b, v73
	v_mul_f32_e32 v74, 0xbfb8aa3b, v74
	v_mul_f32_e32 v75, 0xbfb8aa3b, v75
	v_exp_f32_e32 v72, v72
	v_exp_f32_e32 v73, v73
	v_exp_f32_e32 v74, v74
	v_exp_f32_e32 v75, v75
	v_add_f32_e32 v72, 1.0, v72
	v_add_f32_e32 v73, 1.0, v73
	v_add_f32_e32 v74, 1.0, v74
	v_add_f32_e32 v75, 1.0, v75
	v_rcp_f32_e32 v72, v72
	v_rcp_f32_e32 v73, v73
	v_rcp_f32_e32 v74, v74
	v_rcp_f32_e32 v75, v75
	v_mul_f32_e32 v72, 0xbf1b4598, v72
	v_mul_f32_e32 v73, 0xbf1b4598, v73
	v_mul_f32_e32 v74, 0xbf1b4598, v74
	v_mul_f32_e32 v75, 0xbf1b4598, v75
	v_mul_f32_e32 v72, 0x3fb8aa3b, v72
	v_mul_f32_e32 v73, 0x3fb8aa3b, v73
	v_mul_f32_e32 v74, 0x3fb8aa3b, v74
	v_mul_f32_e32 v75, 0x3fb8aa3b, v75
	v_exp_f32_e32 v76, v72
	v_exp_f32_e32 v77, v73
	v_exp_f32_e32 v78, v74
	v_exp_f32_e32 v79, v75
	v_mov_b32_e32 v80, v76
	v_mov_b32_e32 v81, v77
	v_mov_b32_e32 v82, v78
	v_mov_b32_e32 v83, v79
	s_and_b64 vcc, exec, s[8:9]
	s_mov_b64 s[40:41], -1
	s_cbranch_vccnz .LBB0_878

.LBB0_1077:
	s_andn2_b64 vcc, exec, s[40:41]
	v_mov_b32_e32 v79, v71
	v_mov_b32_e32 v78, v70
	v_mov_b32_e32 v77, v69
	v_mov_b32_e32 v76, v68
	s_cbranch_vccnz .LBB0_1079
	v_lshl_add_u32 v72, v81, 2, s87
	ds_read_b128 v[72:75], v72
	s_waitcnt lgkmcnt(0)
	v_add_f32_e32 v72, v68, v72
	v_add_f32_e32 v73, v69, v73
	v_add_f32_e32 v74, v70, v74
	v_add_f32_e32 v75, v71, v75
	v_mul_f32_e32 v72, 0xbfb8aa3b, v72
	v_mul_f32_e32 v73, 0xbfb8aa3b, v73
	v_mul_f32_e32 v74, 0xbfb8aa3b, v74
	v_mul_f32_e32 v75, 0xbfb8aa3b, v75
	v_exp_f32_e32 v72, v72
	v_exp_f32_e32 v73, v73
	v_exp_f32_e32 v74, v74
	v_exp_f32_e32 v75, v75
	v_add_f32_e32 v72, 1.0, v72
	v_add_f32_e32 v73, 1.0, v73
	v_add_f32_e32 v74, 1.0, v74
	v_add_f32_e32 v75, 1.0, v75
	v_rcp_f32_e32 v76, v72
	v_rcp_f32_e32 v77, v73
	v_rcp_f32_e32 v78, v74
	v_rcp_f32_e32 v79, v75
	v_mov_b64_e32 v[72:73], v[76:77]
	v_mov_b64_e32 v[74:75], v[78:79]

.LBB0_1080:
	v_add_u32_e32 v176, s88, v148
	ds_read_b128 v[72:75], v176
	s_waitcnt lgkmcnt(0)
	v_add_f32_e32 v68, v68, v72
	v_add_f32_e32 v69, v69, v73
	v_add_f32_e32 v70, v70, v74
	v_add_f32_e32 v71, v71, v75
	v_mul_f32_e32 v68, 0xbfb8aa3b, v68
	v_mul_f32_e32 v69, 0xbfb8aa3b, v69
	v_mul_f32_e32 v70, 0xbfb8aa3b, v70
	v_mul_f32_e32 v71, 0xbfb8aa3b, v71
	v_exp_f32_e32 v68, v68
	v_exp_f32_e32 v69, v69
	v_exp_f32_e32 v70, v70
	v_exp_f32_e32 v71, v71
	v_add_f32_e32 v68, 1.0, v68
	v_add_f32_e32 v69, 1.0, v69
	v_add_f32_e32 v70, 1.0, v70
	v_add_f32_e32 v71, 1.0, v71
	v_rcp_f32_e32 v68, v68
	v_rcp_f32_e32 v69, v69
	v_rcp_f32_e32 v70, v70
	v_rcp_f32_e32 v71, v71
	v_mul_f32_e32 v68, 0xbf1b4598, v68
	v_mul_f32_e32 v69, 0xbf1b4598, v69
	v_mul_f32_e32 v70, 0xbf1b4598, v70
	v_mul_f32_e32 v71, 0xbf1b4598, v71
	v_mul_f32_e32 v68, 0x3fb8aa3b, v68
	v_mul_f32_e32 v69, 0x3fb8aa3b, v69
	v_mul_f32_e32 v70, 0x3fb8aa3b, v70
	v_mul_f32_e32 v71, 0x3fb8aa3b, v71
	v_exp_f32_e32 v72, v68
	v_exp_f32_e32 v73, v69
	v_exp_f32_e32 v74, v70
	v_exp_f32_e32 v75, v71
	v_mov_b32_e32 v76, v72
	v_mov_b32_e32 v77, v73
	v_mov_b32_e32 v78, v74
	v_mov_b32_e32 v79, v75
	s_and_b64 vcc, exec, s[8:9]
	s_mov_b64 s[40:41], -1
	s_cbranch_vccnz .LBB0_883

.LBB0_1084:
	s_andn2_b64 vcc, exec, s[40:41]
	v_mov_b32_e32 v75, v67
	v_mov_b32_e32 v74, v66
	v_mov_b32_e32 v73, v65
	v_mov_b32_e32 v72, v64
	s_cbranch_vccnz .LBB0_1086
	v_lshl_add_u32 v68, v77, 2, s87
	ds_read_b128 v[68:71], v68
	s_waitcnt lgkmcnt(0)
	v_add_f32_e32 v68, v64, v68
	v_add_f32_e32 v69, v65, v69
	v_add_f32_e32 v70, v66, v70
	v_add_f32_e32 v71, v67, v71
	v_mul_f32_e32 v68, 0xbfb8aa3b, v68
	v_mul_f32_e32 v69, 0xbfb8aa3b, v69
	v_mul_f32_e32 v70, 0xbfb8aa3b, v70
	v_mul_f32_e32 v71, 0xbfb8aa3b, v71
	v_exp_f32_e32 v68, v68
	v_exp_f32_e32 v69, v69
	v_exp_f32_e32 v70, v70
	v_exp_f32_e32 v71, v71
	v_add_f32_e32 v68, 1.0, v68
	v_add_f32_e32 v69, 1.0, v69
	v_add_f32_e32 v70, 1.0, v70
	v_add_f32_e32 v71, 1.0, v71
	v_rcp_f32_e32 v72, v68
	v_rcp_f32_e32 v73, v69
	v_rcp_f32_e32 v74, v70
	v_rcp_f32_e32 v75, v71
	v_mov_b64_e32 v[68:69], v[72:73]
	v_mov_b64_e32 v[70:71], v[74:75]

.LBB0_1087:
	v_add_u32_e32 v176, s88, v148
	ds_read_b128 v[68:71], v176
	s_waitcnt lgkmcnt(0)
	v_add_f32_e32 v64, v64, v68
	v_add_f32_e32 v65, v65, v69
	v_add_f32_e32 v66, v66, v70
	v_add_f32_e32 v67, v67, v71
	v_mul_f32_e32 v64, 0xbfb8aa3b, v64
	v_mul_f32_e32 v65, 0xbfb8aa3b, v65
	v_mul_f32_e32 v66, 0xbfb8aa3b, v66
	v_mul_f32_e32 v67, 0xbfb8aa3b, v67
	v_exp_f32_e32 v64, v64
	v_exp_f32_e32 v65, v65
	v_exp_f32_e32 v66, v66
	v_exp_f32_e32 v67, v67
	v_add_f32_e32 v64, 1.0, v64
	v_add_f32_e32 v65, 1.0, v65
	v_add_f32_e32 v66, 1.0, v66
	v_add_f32_e32 v67, 1.0, v67
	v_rcp_f32_e32 v64, v64
	v_rcp_f32_e32 v65, v65
	v_rcp_f32_e32 v66, v66
	v_rcp_f32_e32 v67, v67
	v_mul_f32_e32 v64, 0xbf1b4598, v64
	v_mul_f32_e32 v65, 0xbf1b4598, v65
	v_mul_f32_e32 v66, 0xbf1b4598, v66
	v_mul_f32_e32 v67, 0xbf1b4598, v67
	v_mul_f32_e32 v64, 0x3fb8aa3b, v64
	v_mul_f32_e32 v65, 0x3fb8aa3b, v65
	v_mul_f32_e32 v66, 0x3fb8aa3b, v66
	v_mul_f32_e32 v67, 0x3fb8aa3b, v67
	v_exp_f32_e32 v68, v64
	v_exp_f32_e32 v69, v65
	v_exp_f32_e32 v70, v66
	v_exp_f32_e32 v71, v67
	v_mov_b32_e32 v72, v68
	v_mov_b32_e32 v73, v69
	v_mov_b32_e32 v74, v70
	v_mov_b32_e32 v75, v71
	s_and_b64 vcc, exec, s[8:9]
	s_mov_b64 s[40:41], -1
	s_cbranch_vccnz .LBB0_888

.LBB0_1091:
	s_andn2_b64 vcc, exec, s[40:41]
	v_mov_b32_e32 v67, v59
	v_mov_b32_e32 v66, v58
	v_mov_b32_e32 v65, v57
	v_mov_b32_e32 v64, v56
	s_cbranch_vccnz .LBB0_1093
	v_lshl_add_u32 v60, v71, 2, s87
	ds_read_b128 v[60:63], v60
	s_waitcnt lgkmcnt(0)
	v_add_f32_e32 v60, v56, v60
	v_add_f32_e32 v61, v57, v61
	v_add_f32_e32 v62, v58, v62
	v_add_f32_e32 v63, v59, v63
	v_mul_f32_e32 v60, 0xbfb8aa3b, v60
	v_mul_f32_e32 v61, 0xbfb8aa3b, v61
	v_mul_f32_e32 v62, 0xbfb8aa3b, v62
	v_mul_f32_e32 v63, 0xbfb8aa3b, v63
	v_exp_f32_e32 v60, v60
	v_exp_f32_e32 v61, v61
	v_exp_f32_e32 v62, v62
	v_exp_f32_e32 v63, v63
	v_add_f32_e32 v60, 1.0, v60
	v_add_f32_e32 v61, 1.0, v61
	v_add_f32_e32 v62, 1.0, v62
	v_add_f32_e32 v63, 1.0, v63
	v_rcp_f32_e32 v64, v60
	v_rcp_f32_e32 v65, v61
	v_rcp_f32_e32 v66, v62
	v_rcp_f32_e32 v67, v63
	v_mov_b64_e32 v[60:61], v[64:65]
	v_mov_b64_e32 v[62:63], v[66:67]

.LBB0_1094:
	v_add_u32_e32 v176, s88, v148
	ds_read_b128 v[60:63], v176
	s_waitcnt lgkmcnt(0)
	v_add_f32_e32 v56, v56, v60
	v_add_f32_e32 v57, v57, v61
	v_add_f32_e32 v58, v58, v62
	v_add_f32_e32 v59, v59, v63
	v_mul_f32_e32 v56, 0xbfb8aa3b, v56
	v_mul_f32_e32 v57, 0xbfb8aa3b, v57
	v_mul_f32_e32 v58, 0xbfb8aa3b, v58
	v_mul_f32_e32 v59, 0xbfb8aa3b, v59
	v_exp_f32_e32 v56, v56
	v_exp_f32_e32 v57, v57
	v_exp_f32_e32 v58, v58
	v_exp_f32_e32 v59, v59
	v_add_f32_e32 v56, 1.0, v56
	v_add_f32_e32 v57, 1.0, v57
	v_add_f32_e32 v58, 1.0, v58
	v_add_f32_e32 v59, 1.0, v59
	v_rcp_f32_e32 v56, v56
	v_rcp_f32_e32 v57, v57
	v_rcp_f32_e32 v58, v58
	v_rcp_f32_e32 v59, v59
	v_mul_f32_e32 v56, 0xbf1b4598, v56
	v_mul_f32_e32 v57, 0xbf1b4598, v57
	v_mul_f32_e32 v58, 0xbf1b4598, v58
	v_mul_f32_e32 v59, 0xbf1b4598, v59
	v_mul_f32_e32 v56, 0x3fb8aa3b, v56
	v_mul_f32_e32 v57, 0x3fb8aa3b, v57
	v_mul_f32_e32 v58, 0x3fb8aa3b, v58
	v_mul_f32_e32 v59, 0x3fb8aa3b, v59
	v_exp_f32_e32 v60, v56
	v_exp_f32_e32 v61, v57
	v_exp_f32_e32 v62, v58
	v_exp_f32_e32 v63, v59
	v_mov_b32_e32 v64, v60
	v_mov_b32_e32 v65, v61
	v_mov_b32_e32 v66, v62
	v_mov_b32_e32 v67, v63
	s_and_b64 vcc, exec, s[8:9]
	s_mov_b64 s[40:41], -1
	s_cbranch_vccnz .LBB0_906

.LBB0_1098:
	s_andn2_b64 vcc, exec, s[40:41]
	v_mov_b32_e32 v63, v55
	v_mov_b32_e32 v62, v54
	v_mov_b32_e32 v61, v53
	v_mov_b32_e32 v60, v52
	s_cbranch_vccnz .LBB0_1100
	v_lshl_add_u32 v56, v65, 2, s87
	ds_read_b128 v[56:59], v56
	s_waitcnt lgkmcnt(0)
	v_add_f32_e32 v56, v52, v56
	v_add_f32_e32 v57, v53, v57
	v_add_f32_e32 v58, v54, v58
	v_add_f32_e32 v59, v55, v59
	v_mul_f32_e32 v56, 0xbfb8aa3b, v56
	v_mul_f32_e32 v57, 0xbfb8aa3b, v57
	v_mul_f32_e32 v58, 0xbfb8aa3b, v58
	v_mul_f32_e32 v59, 0xbfb8aa3b, v59
	v_exp_f32_e32 v56, v56
	v_exp_f32_e32 v57, v57
	v_exp_f32_e32 v58, v58
	v_exp_f32_e32 v59, v59
	v_add_f32_e32 v56, 1.0, v56
	v_add_f32_e32 v57, 1.0, v57
	v_add_f32_e32 v58, 1.0, v58
	v_add_f32_e32 v59, 1.0, v59
	v_rcp_f32_e32 v60, v56
	v_rcp_f32_e32 v61, v57
	v_rcp_f32_e32 v62, v58
	v_rcp_f32_e32 v63, v59
	v_mov_b64_e32 v[56:57], v[60:61]
	v_mov_b64_e32 v[58:59], v[62:63]

.LBB0_1101:
	v_add_u32_e32 v176, s88, v148
	ds_read_b128 v[56:59], v176
	s_waitcnt lgkmcnt(0)
	v_add_f32_e32 v52, v52, v56
	v_add_f32_e32 v53, v53, v57
	v_add_f32_e32 v54, v54, v58
	v_add_f32_e32 v55, v55, v59
	v_mul_f32_e32 v52, 0xbfb8aa3b, v52
	v_mul_f32_e32 v53, 0xbfb8aa3b, v53
	v_mul_f32_e32 v54, 0xbfb8aa3b, v54
	v_mul_f32_e32 v55, 0xbfb8aa3b, v55
	v_exp_f32_e32 v52, v52
	v_exp_f32_e32 v53, v53
	v_exp_f32_e32 v54, v54
	v_exp_f32_e32 v55, v55
	v_add_f32_e32 v52, 1.0, v52
	v_add_f32_e32 v53, 1.0, v53
	v_add_f32_e32 v54, 1.0, v54
	v_add_f32_e32 v55, 1.0, v55
	v_rcp_f32_e32 v52, v52
	v_rcp_f32_e32 v53, v53
	v_rcp_f32_e32 v54, v54
	v_rcp_f32_e32 v55, v55
	v_mul_f32_e32 v52, 0xbf1b4598, v52
	v_mul_f32_e32 v53, 0xbf1b4598, v53
	v_mul_f32_e32 v54, 0xbf1b4598, v54
	v_mul_f32_e32 v55, 0xbf1b4598, v55
	v_mul_f32_e32 v52, 0x3fb8aa3b, v52
	v_mul_f32_e32 v53, 0x3fb8aa3b, v53
	v_mul_f32_e32 v54, 0x3fb8aa3b, v54
	v_mul_f32_e32 v55, 0x3fb8aa3b, v55
	v_exp_f32_e32 v56, v52
	v_exp_f32_e32 v57, v53
	v_exp_f32_e32 v58, v54
	v_exp_f32_e32 v59, v55
	v_mov_b32_e32 v60, v56
	v_mov_b32_e32 v61, v57
	v_mov_b32_e32 v62, v58
	v_mov_b32_e32 v63, v59
	s_and_b64 vcc, exec, s[8:9]
	s_mov_b64 s[40:41], -1
	s_cbranch_vccnz .LBB0_911

.LBB0_1105:
	s_andn2_b64 vcc, exec, s[40:41]
	v_mov_b32_e32 v59, v51
	v_mov_b32_e32 v58, v50
	v_mov_b32_e32 v57, v49
	v_mov_b32_e32 v56, v48
	s_cbranch_vccnz .LBB0_1107
	v_lshl_add_u32 v52, v61, 2, s87
	ds_read_b128 v[52:55], v52
	s_waitcnt lgkmcnt(0)
	v_add_f32_e32 v52, v48, v52
	v_add_f32_e32 v53, v49, v53
	v_add_f32_e32 v54, v50, v54
	v_add_f32_e32 v55, v51, v55
	v_mul_f32_e32 v52, 0xbfb8aa3b, v52
	v_mul_f32_e32 v53, 0xbfb8aa3b, v53
	v_mul_f32_e32 v54, 0xbfb8aa3b, v54
	v_mul_f32_e32 v55, 0xbfb8aa3b, v55
	v_exp_f32_e32 v52, v52
	v_exp_f32_e32 v53, v53
	v_exp_f32_e32 v54, v54
	v_exp_f32_e32 v55, v55
	v_add_f32_e32 v52, 1.0, v52
	v_add_f32_e32 v53, 1.0, v53
	v_add_f32_e32 v54, 1.0, v54
	v_add_f32_e32 v55, 1.0, v55
	v_rcp_f32_e32 v56, v52
	v_rcp_f32_e32 v57, v53
	v_rcp_f32_e32 v58, v54
	v_rcp_f32_e32 v59, v55
	v_mov_b64_e32 v[52:53], v[56:57]
	v_mov_b64_e32 v[54:55], v[58:59]

.LBB0_1108:
	v_add_u32_e32 v176, s88, v148
	ds_read_b128 v[52:55], v176
	s_waitcnt lgkmcnt(0)
	v_add_f32_e32 v48, v48, v52
	v_add_f32_e32 v49, v49, v53
	v_add_f32_e32 v50, v50, v54
	v_add_f32_e32 v51, v51, v55
	v_mul_f32_e32 v48, 0xbfb8aa3b, v48
	v_mul_f32_e32 v49, 0xbfb8aa3b, v49
	v_mul_f32_e32 v50, 0xbfb8aa3b, v50
	v_mul_f32_e32 v51, 0xbfb8aa3b, v51
	v_exp_f32_e32 v48, v48
	v_exp_f32_e32 v49, v49
	v_exp_f32_e32 v50, v50
	v_exp_f32_e32 v51, v51
	v_add_f32_e32 v48, 1.0, v48
	v_add_f32_e32 v49, 1.0, v49
	v_add_f32_e32 v50, 1.0, v50
	v_add_f32_e32 v51, 1.0, v51
	v_rcp_f32_e32 v48, v48
	v_rcp_f32_e32 v49, v49
	v_rcp_f32_e32 v50, v50
	v_rcp_f32_e32 v51, v51
	v_mul_f32_e32 v48, 0xbf1b4598, v48
	v_mul_f32_e32 v49, 0xbf1b4598, v49
	v_mul_f32_e32 v50, 0xbf1b4598, v50
	v_mul_f32_e32 v51, 0xbf1b4598, v51
	v_mul_f32_e32 v48, 0x3fb8aa3b, v48
	v_mul_f32_e32 v49, 0x3fb8aa3b, v49
	v_mul_f32_e32 v50, 0x3fb8aa3b, v50
	v_mul_f32_e32 v51, 0x3fb8aa3b, v51
	v_exp_f32_e32 v52, v48
	v_exp_f32_e32 v53, v49
	v_exp_f32_e32 v54, v50
	v_exp_f32_e32 v55, v51
	v_mov_b32_e32 v56, v52
	v_mov_b32_e32 v57, v53
	v_mov_b32_e32 v58, v54
	v_mov_b32_e32 v59, v55
	s_and_b64 vcc, exec, s[8:9]
	s_mov_b64 s[40:41], -1
	s_cbranch_vccnz .LBB0_916

.LBB0_1112:
	s_andn2_b64 vcc, exec, s[40:41]
	v_mov_b32_e32 v51, v43
	v_mov_b32_e32 v50, v42
	v_mov_b32_e32 v49, v41
	v_mov_b32_e32 v48, v40
	s_cbranch_vccnz .LBB0_1114
	v_lshl_add_u32 v44, v55, 2, s87
	ds_read_b128 v[44:47], v44
	s_waitcnt lgkmcnt(0)
	v_add_f32_e32 v44, v40, v44
	v_add_f32_e32 v45, v41, v45
	v_add_f32_e32 v46, v42, v46
	v_add_f32_e32 v47, v43, v47
	v_mul_f32_e32 v44, 0xbfb8aa3b, v44
	v_mul_f32_e32 v45, 0xbfb8aa3b, v45
	v_mul_f32_e32 v46, 0xbfb8aa3b, v46
	v_mul_f32_e32 v47, 0xbfb8aa3b, v47
	v_exp_f32_e32 v44, v44
	v_exp_f32_e32 v45, v45
	v_exp_f32_e32 v46, v46
	v_exp_f32_e32 v47, v47
	v_add_f32_e32 v44, 1.0, v44
	v_add_f32_e32 v45, 1.0, v45
	v_add_f32_e32 v46, 1.0, v46
	v_add_f32_e32 v47, 1.0, v47
	v_rcp_f32_e32 v48, v44
	v_rcp_f32_e32 v49, v45
	v_rcp_f32_e32 v50, v46
	v_rcp_f32_e32 v51, v47
	v_mov_b64_e32 v[44:45], v[48:49]
	v_mov_b64_e32 v[46:47], v[50:51]

.LBB0_1115:
	v_add_u32_e32 v176, s88, v148
	ds_read_b128 v[44:47], v176
	s_waitcnt lgkmcnt(0)
	v_add_f32_e32 v40, v40, v44
	v_add_f32_e32 v41, v41, v45
	v_add_f32_e32 v42, v42, v46
	v_add_f32_e32 v43, v43, v47
	v_mul_f32_e32 v40, 0xbfb8aa3b, v40
	v_mul_f32_e32 v41, 0xbfb8aa3b, v41
	v_mul_f32_e32 v42, 0xbfb8aa3b, v42
	v_mul_f32_e32 v43, 0xbfb8aa3b, v43
	v_exp_f32_e32 v40, v40
	v_exp_f32_e32 v41, v41
	v_exp_f32_e32 v42, v42
	v_exp_f32_e32 v43, v43
	v_add_f32_e32 v40, 1.0, v40
	v_add_f32_e32 v41, 1.0, v41
	v_add_f32_e32 v42, 1.0, v42
	v_add_f32_e32 v43, 1.0, v43
	v_rcp_f32_e32 v40, v40
	v_rcp_f32_e32 v41, v41
	v_rcp_f32_e32 v42, v42
	v_rcp_f32_e32 v43, v43
	v_mul_f32_e32 v40, 0xbf1b4598, v40
	v_mul_f32_e32 v41, 0xbf1b4598, v41
	v_mul_f32_e32 v42, 0xbf1b4598, v42
	v_mul_f32_e32 v43, 0xbf1b4598, v43
	v_mul_f32_e32 v40, 0x3fb8aa3b, v40
	v_mul_f32_e32 v41, 0x3fb8aa3b, v41
	v_mul_f32_e32 v42, 0x3fb8aa3b, v42
	v_mul_f32_e32 v43, 0x3fb8aa3b, v43
	v_exp_f32_e32 v44, v40
	v_exp_f32_e32 v45, v41
	v_exp_f32_e32 v46, v42
	v_exp_f32_e32 v47, v43
	v_mov_b32_e32 v48, v44
	v_mov_b32_e32 v49, v45
	v_mov_b32_e32 v50, v46
	v_mov_b32_e32 v51, v47
	s_and_b64 vcc, exec, s[8:9]
	s_mov_b64 s[40:41], -1
	s_cbranch_vccnz .LBB0_934

.LBB0_1119:
	s_andn2_b64 vcc, exec, s[40:41]
	v_mov_b32_e32 v47, v39
	v_mov_b32_e32 v46, v38
	v_mov_b32_e32 v45, v37
	v_mov_b32_e32 v44, v36
	s_cbranch_vccnz .LBB0_1121
	v_lshl_add_u32 v40, v49, 2, s87
	ds_read_b128 v[40:43], v40
	s_waitcnt lgkmcnt(0)
	v_add_f32_e32 v40, v36, v40
	v_add_f32_e32 v41, v37, v41
	v_add_f32_e32 v42, v38, v42
	v_add_f32_e32 v43, v39, v43
	v_mul_f32_e32 v40, 0xbfb8aa3b, v40
	v_mul_f32_e32 v41, 0xbfb8aa3b, v41
	v_mul_f32_e32 v42, 0xbfb8aa3b, v42
	v_mul_f32_e32 v43, 0xbfb8aa3b, v43
	v_exp_f32_e32 v40, v40
	v_exp_f32_e32 v41, v41
	v_exp_f32_e32 v42, v42
	v_exp_f32_e32 v43, v43
	v_add_f32_e32 v40, 1.0, v40
	v_add_f32_e32 v41, 1.0, v41
	v_add_f32_e32 v42, 1.0, v42
	v_add_f32_e32 v43, 1.0, v43
	v_rcp_f32_e32 v44, v40
	v_rcp_f32_e32 v45, v41
	v_rcp_f32_e32 v46, v42
	v_rcp_f32_e32 v47, v43
	v_mov_b64_e32 v[40:41], v[44:45]
	v_mov_b64_e32 v[42:43], v[46:47]

.LBB0_1122:
	v_add_u32_e32 v176, s88, v148
	ds_read_b128 v[40:43], v176
	s_waitcnt lgkmcnt(0)
	v_add_f32_e32 v36, v36, v40
	v_add_f32_e32 v37, v37, v41
	v_add_f32_e32 v38, v38, v42
	v_add_f32_e32 v39, v39, v43
	v_mul_f32_e32 v36, 0xbfb8aa3b, v36
	v_mul_f32_e32 v37, 0xbfb8aa3b, v37
	v_mul_f32_e32 v38, 0xbfb8aa3b, v38
	v_mul_f32_e32 v39, 0xbfb8aa3b, v39
	v_exp_f32_e32 v36, v36
	v_exp_f32_e32 v37, v37
	v_exp_f32_e32 v38, v38
	v_exp_f32_e32 v39, v39
	v_add_f32_e32 v36, 1.0, v36
	v_add_f32_e32 v37, 1.0, v37
	v_add_f32_e32 v38, 1.0, v38
	v_add_f32_e32 v39, 1.0, v39
	v_rcp_f32_e32 v36, v36
	v_rcp_f32_e32 v37, v37
	v_rcp_f32_e32 v38, v38
	v_rcp_f32_e32 v39, v39
	v_mul_f32_e32 v36, 0xbf1b4598, v36
	v_mul_f32_e32 v37, 0xbf1b4598, v37
	v_mul_f32_e32 v38, 0xbf1b4598, v38
	v_mul_f32_e32 v39, 0xbf1b4598, v39
	v_mul_f32_e32 v36, 0x3fb8aa3b, v36
	v_mul_f32_e32 v37, 0x3fb8aa3b, v37
	v_mul_f32_e32 v38, 0x3fb8aa3b, v38
	v_mul_f32_e32 v39, 0x3fb8aa3b, v39
	v_exp_f32_e32 v40, v36
	v_exp_f32_e32 v41, v37
	v_exp_f32_e32 v42, v38
	v_exp_f32_e32 v43, v39
	v_mov_b32_e32 v44, v40
	v_mov_b32_e32 v45, v41
	v_mov_b32_e32 v46, v42
	v_mov_b32_e32 v47, v43
	s_and_b64 vcc, exec, s[8:9]
	s_mov_b64 s[40:41], -1
	s_cbranch_vccnz .LBB0_939

.LBB0_1126:
	s_andn2_b64 vcc, exec, s[40:41]
	v_mov_b32_e32 v43, v35
	v_mov_b32_e32 v42, v34
	v_mov_b32_e32 v41, v33
	v_mov_b32_e32 v40, v32
	s_cbranch_vccnz .LBB0_1128
	v_lshl_add_u32 v36, v45, 2, s87
	ds_read_b128 v[36:39], v36
	s_waitcnt lgkmcnt(0)
	v_add_f32_e32 v36, v32, v36
	v_add_f32_e32 v37, v33, v37
	v_add_f32_e32 v38, v34, v38
	v_add_f32_e32 v39, v35, v39
	v_mul_f32_e32 v36, 0xbfb8aa3b, v36
	v_mul_f32_e32 v37, 0xbfb8aa3b, v37
	v_mul_f32_e32 v38, 0xbfb8aa3b, v38
	v_mul_f32_e32 v39, 0xbfb8aa3b, v39
	v_exp_f32_e32 v36, v36
	v_exp_f32_e32 v37, v37
	v_exp_f32_e32 v38, v38
	v_exp_f32_e32 v39, v39
	v_add_f32_e32 v36, 1.0, v36
	v_add_f32_e32 v37, 1.0, v37
	v_add_f32_e32 v38, 1.0, v38
	v_add_f32_e32 v39, 1.0, v39
	v_rcp_f32_e32 v40, v36
	v_rcp_f32_e32 v41, v37
	v_rcp_f32_e32 v42, v38
	v_rcp_f32_e32 v43, v39
	v_mov_b64_e32 v[36:37], v[40:41]
	v_mov_b64_e32 v[38:39], v[42:43]

.LBB0_1129:
	v_add_u32_e32 v176, s88, v148
	ds_read_b128 v[36:39], v176
	s_waitcnt lgkmcnt(0)
	v_add_f32_e32 v32, v32, v36
	v_add_f32_e32 v33, v33, v37
	v_add_f32_e32 v34, v34, v38
	v_add_f32_e32 v35, v35, v39
	v_mul_f32_e32 v32, 0xbfb8aa3b, v32
	v_mul_f32_e32 v33, 0xbfb8aa3b, v33
	v_mul_f32_e32 v34, 0xbfb8aa3b, v34
	v_mul_f32_e32 v35, 0xbfb8aa3b, v35
	v_exp_f32_e32 v32, v32
	v_exp_f32_e32 v33, v33
	v_exp_f32_e32 v34, v34
	v_exp_f32_e32 v35, v35
	v_add_f32_e32 v32, 1.0, v32
	v_add_f32_e32 v33, 1.0, v33
	v_add_f32_e32 v34, 1.0, v34
	v_add_f32_e32 v35, 1.0, v35
	v_rcp_f32_e32 v32, v32
	v_rcp_f32_e32 v33, v33
	v_rcp_f32_e32 v34, v34
	v_rcp_f32_e32 v35, v35
	v_mul_f32_e32 v32, 0xbf1b4598, v32
	v_mul_f32_e32 v33, 0xbf1b4598, v33
	v_mul_f32_e32 v34, 0xbf1b4598, v34
	v_mul_f32_e32 v35, 0xbf1b4598, v35
	v_mul_f32_e32 v32, 0x3fb8aa3b, v32
	v_mul_f32_e32 v33, 0x3fb8aa3b, v33
	v_mul_f32_e32 v34, 0x3fb8aa3b, v34
	v_mul_f32_e32 v35, 0x3fb8aa3b, v35
	v_exp_f32_e32 v36, v32
	v_exp_f32_e32 v37, v33
	v_exp_f32_e32 v38, v34
	v_exp_f32_e32 v39, v35
	v_mov_b32_e32 v40, v36
	v_mov_b32_e32 v41, v37
	v_mov_b32_e32 v42, v38
	v_mov_b32_e32 v43, v39
	s_and_b64 vcc, exec, s[8:9]
	s_mov_b64 s[40:41], -1
	s_cbranch_vccnz .LBB0_944

.LBB0_1133:
	s_andn2_b64 vcc, exec, s[40:41]
	v_mov_b32_e32 v35, v27
	v_mov_b32_e32 v34, v26
	v_mov_b32_e32 v33, v25
	v_mov_b32_e32 v32, v24
	s_cbranch_vccnz .LBB0_1135
	v_lshl_add_u32 v28, v39, 2, s87
	ds_read_b128 v[28:31], v28
	s_waitcnt lgkmcnt(0)
	v_add_f32_e32 v28, v24, v28
	v_add_f32_e32 v29, v25, v29
	v_add_f32_e32 v30, v26, v30
	v_add_f32_e32 v31, v27, v31
	v_mul_f32_e32 v28, 0xbfb8aa3b, v28
	v_mul_f32_e32 v29, 0xbfb8aa3b, v29
	v_mul_f32_e32 v30, 0xbfb8aa3b, v30
	v_mul_f32_e32 v31, 0xbfb8aa3b, v31
	v_exp_f32_e32 v28, v28
	v_exp_f32_e32 v29, v29
	v_exp_f32_e32 v30, v30
	v_exp_f32_e32 v31, v31
	v_add_f32_e32 v28, 1.0, v28
	v_add_f32_e32 v29, 1.0, v29
	v_add_f32_e32 v30, 1.0, v30
	v_add_f32_e32 v31, 1.0, v31
	v_rcp_f32_e32 v32, v28
	v_rcp_f32_e32 v33, v29
	v_rcp_f32_e32 v34, v30
	v_rcp_f32_e32 v35, v31
	v_mov_b64_e32 v[28:29], v[32:33]
	v_mov_b64_e32 v[30:31], v[34:35]

.LBB0_1136:
	v_add_u32_e32 v176, s88, v148
	ds_read_b128 v[28:31], v176
	s_waitcnt lgkmcnt(0)
	v_add_f32_e32 v24, v24, v28
	v_add_f32_e32 v25, v25, v29
	v_add_f32_e32 v26, v26, v30
	v_add_f32_e32 v27, v27, v31
	v_mul_f32_e32 v24, 0xbfb8aa3b, v24
	v_mul_f32_e32 v25, 0xbfb8aa3b, v25
	v_mul_f32_e32 v26, 0xbfb8aa3b, v26
	v_mul_f32_e32 v27, 0xbfb8aa3b, v27
	v_exp_f32_e32 v24, v24
	v_exp_f32_e32 v25, v25
	v_exp_f32_e32 v26, v26
	v_exp_f32_e32 v27, v27
	v_add_f32_e32 v24, 1.0, v24
	v_add_f32_e32 v25, 1.0, v25
	v_add_f32_e32 v26, 1.0, v26
	v_add_f32_e32 v27, 1.0, v27
	v_rcp_f32_e32 v24, v24
	v_rcp_f32_e32 v25, v25
	v_rcp_f32_e32 v26, v26
	v_rcp_f32_e32 v27, v27
	v_mul_f32_e32 v24, 0xbf1b4598, v24
	v_mul_f32_e32 v25, 0xbf1b4598, v25
	v_mul_f32_e32 v26, 0xbf1b4598, v26
	v_mul_f32_e32 v27, 0xbf1b4598, v27
	v_mul_f32_e32 v24, 0x3fb8aa3b, v24
	v_mul_f32_e32 v25, 0x3fb8aa3b, v25
	v_mul_f32_e32 v26, 0x3fb8aa3b, v26
	v_mul_f32_e32 v27, 0x3fb8aa3b, v27
	v_exp_f32_e32 v28, v24
	v_exp_f32_e32 v29, v25
	v_exp_f32_e32 v30, v26
	v_exp_f32_e32 v31, v27
	v_mov_b32_e32 v32, v28
	v_mov_b32_e32 v33, v29
	v_mov_b32_e32 v34, v30
	v_mov_b32_e32 v35, v31
	s_and_b64 vcc, exec, s[8:9]
	s_mov_b64 s[40:41], -1
	s_cbranch_vccnz .LBB0_962

.LBB0_1140:
	s_andn2_b64 vcc, exec, s[40:41]
	v_mov_b32_e32 v31, v23
	v_mov_b32_e32 v30, v22
	v_mov_b32_e32 v29, v21
	v_mov_b32_e32 v28, v20
	s_cbranch_vccnz .LBB0_1142
	v_lshl_add_u32 v24, v33, 2, s87
	ds_read_b128 v[24:27], v24
	s_waitcnt lgkmcnt(0)
	v_add_f32_e32 v24, v20, v24
	v_add_f32_e32 v25, v21, v25
	v_add_f32_e32 v26, v22, v26
	v_add_f32_e32 v27, v23, v27
	v_mul_f32_e32 v24, 0xbfb8aa3b, v24
	v_mul_f32_e32 v25, 0xbfb8aa3b, v25
	v_mul_f32_e32 v26, 0xbfb8aa3b, v26
	v_mul_f32_e32 v27, 0xbfb8aa3b, v27
	v_exp_f32_e32 v24, v24
	v_exp_f32_e32 v25, v25
	v_exp_f32_e32 v26, v26
	v_exp_f32_e32 v27, v27
	v_add_f32_e32 v24, 1.0, v24
	v_add_f32_e32 v25, 1.0, v25
	v_add_f32_e32 v26, 1.0, v26
	v_add_f32_e32 v27, 1.0, v27
	v_rcp_f32_e32 v28, v24
	v_rcp_f32_e32 v29, v25
	v_rcp_f32_e32 v30, v26
	v_rcp_f32_e32 v31, v27
	v_mov_b64_e32 v[24:25], v[28:29]
	v_mov_b64_e32 v[26:27], v[30:31]

.LBB0_1143:
	v_add_u32_e32 v176, s88, v148
	ds_read_b128 v[24:27], v176
	s_waitcnt lgkmcnt(0)
	v_add_f32_e32 v20, v20, v24
	v_add_f32_e32 v21, v21, v25
	v_add_f32_e32 v22, v22, v26
	v_add_f32_e32 v23, v23, v27
	v_mul_f32_e32 v20, 0xbfb8aa3b, v20
	v_mul_f32_e32 v21, 0xbfb8aa3b, v21
	v_mul_f32_e32 v22, 0xbfb8aa3b, v22
	v_mul_f32_e32 v23, 0xbfb8aa3b, v23
	v_exp_f32_e32 v20, v20
	v_exp_f32_e32 v21, v21
	v_exp_f32_e32 v22, v22
	v_exp_f32_e32 v23, v23
	v_add_f32_e32 v20, 1.0, v20
	v_add_f32_e32 v21, 1.0, v21
	v_add_f32_e32 v22, 1.0, v22
	v_add_f32_e32 v23, 1.0, v23
	v_rcp_f32_e32 v20, v20
	v_rcp_f32_e32 v21, v21
	v_rcp_f32_e32 v22, v22
	v_rcp_f32_e32 v23, v23
	v_mul_f32_e32 v20, 0xbf1b4598, v20
	v_mul_f32_e32 v21, 0xbf1b4598, v21
	v_mul_f32_e32 v22, 0xbf1b4598, v22
	v_mul_f32_e32 v23, 0xbf1b4598, v23
	v_mul_f32_e32 v20, 0x3fb8aa3b, v20
	v_mul_f32_e32 v21, 0x3fb8aa3b, v21
	v_mul_f32_e32 v22, 0x3fb8aa3b, v22
	v_mul_f32_e32 v23, 0x3fb8aa3b, v23
	v_exp_f32_e32 v24, v20
	v_exp_f32_e32 v25, v21
	v_exp_f32_e32 v26, v22
	v_exp_f32_e32 v27, v23
	v_mov_b32_e32 v28, v24
	v_mov_b32_e32 v29, v25
	v_mov_b32_e32 v30, v26
	v_mov_b32_e32 v31, v27
	s_and_b64 vcc, exec, s[8:9]
	s_mov_b64 s[40:41], -1
	s_cbranch_vccnz .LBB0_967

.LBB0_1147:
	s_andn2_b64 vcc, exec, s[40:41]
	v_mov_b32_e32 v27, v19
	v_mov_b32_e32 v26, v18
	v_mov_b32_e32 v25, v17
	v_mov_b32_e32 v24, v16
	s_cbranch_vccnz .LBB0_1149
	v_lshl_add_u32 v20, v29, 2, s87
	ds_read_b128 v[20:23], v20
	s_waitcnt lgkmcnt(0)
	v_add_f32_e32 v20, v16, v20
	v_add_f32_e32 v21, v17, v21
	v_add_f32_e32 v22, v18, v22
	v_add_f32_e32 v23, v19, v23
	v_mul_f32_e32 v20, 0xbfb8aa3b, v20
	v_mul_f32_e32 v21, 0xbfb8aa3b, v21
	v_mul_f32_e32 v22, 0xbfb8aa3b, v22
	v_mul_f32_e32 v23, 0xbfb8aa3b, v23
	v_exp_f32_e32 v20, v20
	v_exp_f32_e32 v21, v21
	v_exp_f32_e32 v22, v22
	v_exp_f32_e32 v23, v23
	v_add_f32_e32 v20, 1.0, v20
	v_add_f32_e32 v21, 1.0, v21
	v_add_f32_e32 v22, 1.0, v22
	v_add_f32_e32 v23, 1.0, v23
	v_rcp_f32_e32 v24, v20
	v_rcp_f32_e32 v25, v21
	v_rcp_f32_e32 v26, v22
	v_rcp_f32_e32 v27, v23
	v_mov_b64_e32 v[20:21], v[24:25]
	v_mov_b64_e32 v[22:23], v[26:27]

.LBB0_1150:
	v_add_u32_e32 v176, s88, v148
	ds_read_b128 v[20:23], v176
	s_waitcnt lgkmcnt(0)
	v_add_f32_e32 v16, v16, v20
	v_add_f32_e32 v17, v17, v21
	v_add_f32_e32 v18, v18, v22
	v_add_f32_e32 v19, v19, v23
	v_mul_f32_e32 v16, 0xbfb8aa3b, v16
	v_mul_f32_e32 v17, 0xbfb8aa3b, v17
	v_mul_f32_e32 v18, 0xbfb8aa3b, v18
	v_mul_f32_e32 v19, 0xbfb8aa3b, v19
	v_exp_f32_e32 v16, v16
	v_exp_f32_e32 v17, v17
	v_exp_f32_e32 v18, v18
	v_exp_f32_e32 v19, v19
	v_add_f32_e32 v16, 1.0, v16
	v_add_f32_e32 v17, 1.0, v17
	v_add_f32_e32 v18, 1.0, v18
	v_add_f32_e32 v19, 1.0, v19
	v_rcp_f32_e32 v16, v16
	v_rcp_f32_e32 v17, v17
	v_rcp_f32_e32 v18, v18
	v_rcp_f32_e32 v19, v19
	v_mul_f32_e32 v16, 0xbf1b4598, v16
	v_mul_f32_e32 v17, 0xbf1b4598, v17
	v_mul_f32_e32 v18, 0xbf1b4598, v18
	v_mul_f32_e32 v19, 0xbf1b4598, v19
	v_mul_f32_e32 v16, 0x3fb8aa3b, v16
	v_mul_f32_e32 v17, 0x3fb8aa3b, v17
	v_mul_f32_e32 v18, 0x3fb8aa3b, v18
	v_mul_f32_e32 v19, 0x3fb8aa3b, v19
	v_exp_f32_e32 v20, v16
	v_exp_f32_e32 v21, v17
	v_exp_f32_e32 v22, v18
	v_exp_f32_e32 v23, v19
	v_mov_b32_e32 v24, v20
	v_mov_b32_e32 v25, v21
	v_mov_b32_e32 v26, v22
	v_mov_b32_e32 v27, v23
	s_and_b64 vcc, exec, s[8:9]
	s_mov_b64 s[40:41], -1
	s_cbranch_vccnz .LBB0_972

.LBB0_1154:
	s_andn2_b64 vcc, exec, s[40:41]
	v_mov_b32_e32 v19, v11
	v_mov_b32_e32 v18, v10
	v_mov_b32_e32 v17, v9
	v_mov_b32_e32 v16, v8
	s_cbranch_vccnz .LBB0_1156
	v_lshl_add_u32 v12, v23, 2, s87
	ds_read_b128 v[12:15], v12
	s_waitcnt lgkmcnt(0)
	v_add_f32_e32 v12, v8, v12
	v_add_f32_e32 v13, v9, v13
	v_add_f32_e32 v14, v10, v14
	v_add_f32_e32 v15, v11, v15
	v_mul_f32_e32 v12, 0xbfb8aa3b, v12
	v_mul_f32_e32 v13, 0xbfb8aa3b, v13
	v_mul_f32_e32 v14, 0xbfb8aa3b, v14
	v_mul_f32_e32 v15, 0xbfb8aa3b, v15
	v_exp_f32_e32 v12, v12
	v_exp_f32_e32 v13, v13
	v_exp_f32_e32 v14, v14
	v_exp_f32_e32 v15, v15
	v_add_f32_e32 v12, 1.0, v12
	v_add_f32_e32 v13, 1.0, v13
	v_add_f32_e32 v14, 1.0, v14
	v_add_f32_e32 v15, 1.0, v15
	v_rcp_f32_e32 v16, v12
	v_rcp_f32_e32 v17, v13
	v_rcp_f32_e32 v18, v14
	v_rcp_f32_e32 v19, v15
	v_mov_b64_e32 v[12:13], v[16:17]
	v_mov_b64_e32 v[14:15], v[18:19]

.LBB0_1157:
	v_add_u32_e32 v176, s88, v148
	ds_read_b128 v[12:15], v176
	s_waitcnt lgkmcnt(0)
	v_add_f32_e32 v8, v8, v12
	v_add_f32_e32 v9, v9, v13
	v_add_f32_e32 v10, v10, v14
	v_add_f32_e32 v11, v11, v15
	v_mul_f32_e32 v8, 0xbfb8aa3b, v8
	v_mul_f32_e32 v9, 0xbfb8aa3b, v9
	v_mul_f32_e32 v10, 0xbfb8aa3b, v10
	v_mul_f32_e32 v11, 0xbfb8aa3b, v11
	v_exp_f32_e32 v8, v8
	v_exp_f32_e32 v9, v9
	v_exp_f32_e32 v10, v10
	v_exp_f32_e32 v11, v11
	v_add_f32_e32 v8, 1.0, v8
	v_add_f32_e32 v9, 1.0, v9
	v_add_f32_e32 v10, 1.0, v10
	v_add_f32_e32 v11, 1.0, v11
	v_rcp_f32_e32 v8, v8
	v_rcp_f32_e32 v9, v9
	v_rcp_f32_e32 v10, v10
	v_rcp_f32_e32 v11, v11
	v_mul_f32_e32 v8, 0xbf1b4598, v8
	v_mul_f32_e32 v9, 0xbf1b4598, v9
	v_mul_f32_e32 v10, 0xbf1b4598, v10
	v_mul_f32_e32 v11, 0xbf1b4598, v11
	v_mul_f32_e32 v8, 0x3fb8aa3b, v8
	v_mul_f32_e32 v9, 0x3fb8aa3b, v9
	v_mul_f32_e32 v10, 0x3fb8aa3b, v10
	v_mul_f32_e32 v11, 0x3fb8aa3b, v11
	v_exp_f32_e32 v12, v8
	v_exp_f32_e32 v13, v9
	v_exp_f32_e32 v14, v10
	v_exp_f32_e32 v15, v11
	v_mov_b32_e32 v16, v12
	v_mov_b32_e32 v17, v13
	v_mov_b32_e32 v18, v14
	v_mov_b32_e32 v19, v15
	s_and_b64 vcc, exec, s[8:9]
	s_mov_b64 s[40:41], -1
	s_cbranch_vccnz .LBB0_990

.LBB0_1161:
	s_andn2_b64 vcc, exec, s[40:41]
	v_mov_b32_e32 v15, v7
	v_mov_b32_e32 v14, v6
	v_mov_b32_e32 v13, v5
	v_mov_b32_e32 v12, v4
	s_cbranch_vccnz .LBB0_1163
	v_lshl_add_u32 v8, v17, 2, s87
	ds_read_b128 v[8:11], v8
	s_waitcnt lgkmcnt(0)
	v_add_f32_e32 v8, v4, v8
	v_add_f32_e32 v9, v5, v9
	v_add_f32_e32 v10, v6, v10
	v_add_f32_e32 v11, v7, v11
	v_mul_f32_e32 v8, 0xbfb8aa3b, v8
	v_mul_f32_e32 v9, 0xbfb8aa3b, v9
	v_mul_f32_e32 v10, 0xbfb8aa3b, v10
	v_mul_f32_e32 v11, 0xbfb8aa3b, v11
	v_exp_f32_e32 v8, v8
	v_exp_f32_e32 v9, v9
	v_exp_f32_e32 v10, v10
	v_exp_f32_e32 v11, v11
	v_add_f32_e32 v8, 1.0, v8
	v_add_f32_e32 v9, 1.0, v9
	v_add_f32_e32 v10, 1.0, v10
	v_add_f32_e32 v11, 1.0, v11
	v_rcp_f32_e32 v12, v8
	v_rcp_f32_e32 v13, v9
	v_rcp_f32_e32 v14, v10
	v_rcp_f32_e32 v15, v11
	v_mov_b64_e32 v[8:9], v[12:13]
	v_mov_b64_e32 v[10:11], v[14:15]

.LBB0_1164:
	v_add_u32_e32 v176, s88, v148
	ds_read_b128 v[8:11], v176
	s_waitcnt lgkmcnt(0)
	v_add_f32_e32 v4, v4, v8
	v_add_f32_e32 v5, v5, v9
	v_add_f32_e32 v6, v6, v10
	v_add_f32_e32 v7, v7, v11
	v_mul_f32_e32 v4, 0xbfb8aa3b, v4
	v_mul_f32_e32 v5, 0xbfb8aa3b, v5
	v_mul_f32_e32 v6, 0xbfb8aa3b, v6
	v_mul_f32_e32 v7, 0xbfb8aa3b, v7
	v_exp_f32_e32 v4, v4
	v_exp_f32_e32 v5, v5
	v_exp_f32_e32 v6, v6
	v_exp_f32_e32 v7, v7
	v_add_f32_e32 v4, 1.0, v4
	v_add_f32_e32 v5, 1.0, v5
	v_add_f32_e32 v6, 1.0, v6
	v_add_f32_e32 v7, 1.0, v7
	v_rcp_f32_e32 v4, v4
	v_rcp_f32_e32 v5, v5
	v_rcp_f32_e32 v6, v6
	v_rcp_f32_e32 v7, v7
	v_mul_f32_e32 v4, 0xbf1b4598, v4
	v_mul_f32_e32 v5, 0xbf1b4598, v5
	v_mul_f32_e32 v6, 0xbf1b4598, v6
	v_mul_f32_e32 v7, 0xbf1b4598, v7
	v_mul_f32_e32 v4, 0x3fb8aa3b, v4
	v_mul_f32_e32 v5, 0x3fb8aa3b, v5
	v_mul_f32_e32 v6, 0x3fb8aa3b, v6
	v_mul_f32_e32 v7, 0x3fb8aa3b, v7
	v_exp_f32_e32 v8, v4
	v_exp_f32_e32 v9, v5
	v_exp_f32_e32 v10, v6
	v_exp_f32_e32 v11, v7
	v_mov_b32_e32 v12, v8
	v_mov_b32_e32 v13, v9
	v_mov_b32_e32 v14, v10
	v_mov_b32_e32 v15, v11
	s_and_b64 vcc, exec, s[8:9]
	s_mov_b64 s[40:41], -1
	s_cbranch_vccnz .LBB0_995

.LBB0_1168:
	s_andn2_b64 vcc, exec, s[10:11]
	v_mov_b32_e32 v11, v3
	v_mov_b32_e32 v10, v2
	v_mov_b32_e32 v9, v1
	v_mov_b32_e32 v8, v0
	s_cbranch_vccnz .LBB0_1170
	v_lshl_add_u32 v4, v13, 2, s87
	ds_read_b128 v[4:7], v4
	s_waitcnt lgkmcnt(0)
	v_add_f32_e32 v4, v0, v4
	v_add_f32_e32 v5, v1, v5
	v_add_f32_e32 v6, v2, v6
	v_add_f32_e32 v7, v3, v7
	v_mul_f32_e32 v4, 0xbfb8aa3b, v4
	v_mul_f32_e32 v5, 0xbfb8aa3b, v5
	v_mul_f32_e32 v6, 0xbfb8aa3b, v6
	v_mul_f32_e32 v7, 0xbfb8aa3b, v7
	v_exp_f32_e32 v4, v4
	v_exp_f32_e32 v5, v5
	v_exp_f32_e32 v6, v6
	v_exp_f32_e32 v7, v7
	v_add_f32_e32 v4, 1.0, v4
	v_add_f32_e32 v5, 1.0, v5
	v_add_f32_e32 v6, 1.0, v6
	v_add_f32_e32 v7, 1.0, v7
	v_rcp_f32_e32 v8, v4
	v_rcp_f32_e32 v9, v5
	v_rcp_f32_e32 v10, v6
	v_rcp_f32_e32 v11, v7
	v_mov_b64_e32 v[4:5], v[8:9]
	v_mov_b64_e32 v[6:7], v[10:11]

.LBB0_1171:
	v_add_u32_e32 v176, s88, v148
	ds_read_b128 v[4:7], v176
	s_waitcnt lgkmcnt(0)
	v_add_f32_e32 v0, v0, v4
	v_add_f32_e32 v1, v1, v5
	v_add_f32_e32 v2, v2, v6
	v_add_f32_e32 v3, v3, v7
	v_mul_f32_e32 v0, 0xbfb8aa3b, v0
	v_mul_f32_e32 v1, 0xbfb8aa3b, v1
	v_mul_f32_e32 v2, 0xbfb8aa3b, v2
	v_mul_f32_e32 v3, 0xbfb8aa3b, v3
	v_exp_f32_e32 v0, v0
	v_exp_f32_e32 v1, v1
	v_exp_f32_e32 v2, v2
	v_exp_f32_e32 v3, v3
	v_add_f32_e32 v0, 1.0, v0
	v_add_f32_e32 v1, 1.0, v1
	v_add_f32_e32 v2, 1.0, v2
	v_add_f32_e32 v3, 1.0, v3
	v_rcp_f32_e32 v0, v0
	v_rcp_f32_e32 v1, v1
	v_rcp_f32_e32 v2, v2
	v_rcp_f32_e32 v3, v3
	v_mul_f32_e32 v0, 0xbf1b4598, v0
	v_mul_f32_e32 v1, 0xbf1b4598, v1
	v_mul_f32_e32 v2, 0xbf1b4598, v2
	v_mul_f32_e32 v3, 0xbf1b4598, v3
	v_mul_f32_e32 v0, 0x3fb8aa3b, v0
	v_mul_f32_e32 v1, 0x3fb8aa3b, v1
	v_mul_f32_e32 v2, 0x3fb8aa3b, v2
	v_mul_f32_e32 v3, 0x3fb8aa3b, v3
	v_exp_f32_e32 v4, v0
	v_exp_f32_e32 v5, v1
	v_exp_f32_e32 v6, v2
	v_exp_f32_e32 v7, v3
	v_mov_b32_e32 v8, v4
	v_mov_b32_e32 v9, v5
	v_mov_b32_e32 v10, v6
	v_mov_b32_e32 v11, v7
	s_and_b64 vcc, exec, s[8:9]
	s_mov_b64 s[8:9], -1
	s_cbranch_vccnz .LBB0_1000

	.amdhsa_kernel _Z14fwd_megakernel6Params
		.amdhsa_group_segment_fixed_size 8192
		.amdhsa_private_segment_fixed_size 0
		.amdhsa_kernarg_size 640
		.amdhsa_user_sgpr_count 2
		.amdhsa_user_sgpr_dispatch_ptr 0
		.amdhsa_user_sgpr_queue_ptr 0
		.amdhsa_user_sgpr_kernarg_segment_ptr 1
		.amdhsa_user_sgpr_dispatch_id 0
		.amdhsa_user_sgpr_kernarg_preload_length 0
		.amdhsa_user_sgpr_kernarg_preload_offset 0
		.amdhsa_user_sgpr_private_segment_size 0
		.amdhsa_uses_dynamic_stack 0
		.amdhsa_enable_private_segment 0
		.amdhsa_system_sgpr_workgroup_id_x 1
		.amdhsa_system_sgpr_workgroup_id_y 0
		.amdhsa_system_sgpr_workgroup_id_z 0
		.amdhsa_system_sgpr_workgroup_info 0
		.amdhsa_system_vgpr_workitem_id 2
		.amdhsa_next_free_vgpr 252
		.amdhsa_next_free_sgpr 94
		.amdhsa_accum_offset 252
		.amdhsa_reserve_vcc 1
		.amdhsa_float_round_mode_32 0
		.amdhsa_float_round_mode_16_64 0
		.amdhsa_float_denorm_mode_32 3
		.amdhsa_float_denorm_mode_16_64 3
		.amdhsa_dx10_clamp 1
		.amdhsa_ieee_mode 1
		.amdhsa_fp16_overflow 0
		.amdhsa_tg_split 0
		.amdhsa_exception_fp_ieee_invalid_op 0
		.amdhsa_exception_fp_denorm_src 0
		.amdhsa_exception_fp_ieee_div_zero 0
		.amdhsa_exception_fp_ieee_overflow 0
		.amdhsa_exception_fp_ieee_underflow 0
		.amdhsa_exception_fp_ieee_inexact 0
		.amdhsa_exception_int_div_zero 0
	.end_amdhsa_kernel

amdhsa.kernels:
  - .agpr_count:     0
    .args:
      - .offset:         0
        .size:           384
        .value_kind:     by_value
      - .offset:         384
        .size:           4
        .value_kind:     hidden_block_count_x
      - .offset:         388
        .size:           4
        .value_kind:     hidden_block_count_y
      - .offset:         392
        .size:           4
        .value_kind:     hidden_block_count_z
      - .offset:         396
        .size:           2
        .value_kind:     hidden_group_size_x
      - .offset:         398
        .size:           2
        .value_kind:     hidden_group_size_y
      - .offset:         400
        .size:           2
        .value_kind:     hidden_group_size_z
      - .offset:         402
        .size:           2
        .value_kind:     hidden_remainder_x
      - .offset:         404
        .size:           2
        .value_kind:     hidden_remainder_y
      - .offset:         406
        .size:           2
        .value_kind:     hidden_remainder_z
      - .offset:         424
        .size:           8
        .value_kind:     hidden_global_offset_x
      - .offset:         432
        .size:           8
        .value_kind:     hidden_global_offset_y
      - .offset:         440
        .size:           8
        .value_kind:     hidden_global_offset_z
      - .offset:         448
        .size:           2
        .value_kind:     hidden_grid_dims
      - .offset:         472
        .size:           8
        .value_kind:     hidden_multigrid_sync_arg
      - .offset:         504
        .size:           4
        .value_kind:     hidden_dynamic_lds_size
    .group_segment_fixed_size: 8192
    .kernarg_segment_align: 8
    .kernarg_segment_size: 640
    .language:       OpenCL C
    .language_version:
      - 2
      - 0
    .max_flat_workgroup_size: 512
    .name:           _Z14fwd_megakernel6Params
    .private_segment_fixed_size: 0
    .sgpr_count:     100
    .sgpr_spill_count: 0
    .symbol:         _Z14fwd_megakernel6Params.kd
    .uniform_work_group_size: 1
    .uses_dynamic_stack: false
    .vgpr_count:     252
    .vgpr_spill_count: 0
    .wavefront_size: 64
